# v121 + M0-DIET: each LDS-DMA destination set by one s_add_i32 m0, base, const; 8 scalar instructions per K-loop iteration removed in all three GEMM loops
# speedup vs baseline: 1.0023x; 1.0018x over previous
; #define PG8_STAGE(bufoff, gbase, voff) do { _Pragma("unroll") for (int _i = 0; _i < 2; ++_i) \
;         __builtin_amdgcn_global_load_lds((const unsigned*)((const char*)(gbase) + (voff)[_i]), (PG8_LAS unsigned*)(lds + (bufoff) + ldsw + _i * 8192), 16, 0, 0); } while (0)
; #define PG8_LDA(dst, b, h) do { _Pragma("unroll") for (int m = 0; m < 4; ++m) _Pragma("unroll") for (int k = 0; k < 2; ++k) dst[m][k] = *(const PG8_LAS bf16x8*)(lds + PG8_SA(b, h) + aoff + m * 2048 + k * 1024); } while (0)
; #define PG8_LDB(dst, b, h) do { _Pragma("unroll") for (int n = 0; n < 2; ++n) _Pragma("unroll") for (int k = 0; k < 2; ++k) dst[n][k] = *(const PG8_LAS bf16x8*)(lds + PG8_SB(b, h) + boff + n * 2048 + k * 1024); } while (0)
; #define PG8_MMA(ai, bj, At, Bt) do { __builtin_amdgcn_s_setprio(1); _Pragma("unroll") for (int m = 0; m < 4; ++m) _Pragma("unroll") for (int n = 0; n < 2; ++n) _Pragma("unroll") for (int k = 0; k < 2; ++k) \
;         acc[ai][bj][m][n] = __builtin_amdgcn_mfma_f32_16x16x32_bf16(Bt[n][k], At[m][k], acc[ai][bj][m][n], 0, 0, 0); __builtin_amdgcn_s_setprio(0); } while (0)
; #define PG8_BAR __builtin_amdgcn_s_barrier()
; template <class Epi, class Sched, bool ALIGN_EPI = false, bool SP2 = false>
; __device__ __forceinline__ void gemm_phase(PG8_LAS unsigned char* lds, const Gemm g, const Sched& S, const Epi& E) {
;     ...
;         const bool has_next = S.next(ui + 1, nxt);
;         const char* nA = has_next ? (const char*)g.A + (size_t)nxt.pm * tstep : cA; const char* nB = has_next ? (const char*)g.Bt + (size_t)nxt.pn * tstep : cB;
;         for (int t = 0; t < nt; t += 2) {
;             const bool last = (t == nt - 2);
;             const char* a1 = cA + (size_t)(t + 1) * kstep;
;             const char* a2 = last ? nA : cA + (size_t)(t + 2) * kstep; const char* b2 = last ? nB : cB + (size_t)(t + 2) * kstep;
;             const char* a3 = a2 + kstep; const char* b3 = b2 + kstep;
;             if (last && has_next) S.a_ready(nxt);
;             if constexpr (SP2) {
;             PG8_LDB(B0, 0, 0); PG8_LDB(B1, 0, 1); PG8_SCHED; PG8_LDA(At, 0, 0); PG8_STAGE(PG8_SA(1, 1), a1 + hstep, voffA);
;             PG8_WAIT_V(8); PG8_WAIT_L(0); PG8_BAR; PG8_MMA(0, 0, At, B0); PG8_MMA(0, 1, At, B1); PG8_BAR; PG8_SCHED;
;             PG8_LDA(At, 0, 1); PG8_STAGE(PG8_SB(0, 0), b2, voffB); PG8_STAGE(PG8_SB(0, 1), b2 + hstep, voffB); PG8_STAGE(PG8_SA(0, 0), a2, voffA);
.LBB0_1129:
	s_ashr_i32 s79, s78, 31
	s_lshl_b64 s[22:23], s[78:79], 19
	v_readlane_b32 s5, v255, 15
	s_add_u32 s80, s5, s22
	s_addc_u32 s81, s61, s23
	s_and_b64 s[22:23], s[2:3], exec
	s_cselect_b32 s5, s81, s7
	s_cselect_b32 s9, s80, s6
	s_ashr_i32 s77, s76, 31
	s_lshl_b64 s[22:23], s[76:77], 19
	s_add_u32 s82, s55, s22
	s_addc_u32 s83, s56, s23
	s_and_b64 s[22:23], s[2:3], exec
	s_cselect_b32 s22, s83, s11
	s_cselect_b32 s23, s82, s10
	s_add_u32 s6, s6, 0xc000
	s_addc_u32 s7, s7, 0
	s_add_u32 s30, s10, 0x10000
	v_mov_b32_e32 v0, 0
	s_addc_u32 s37, s11, 0
	s_mov_b32 s40, -2
	v_add_u32_e32 v246, 0x10000, v192
	s_add_u32 s10, s6, 0x4000
	s_addc_u32 s11, s7, 0
	s_cmp_eq_u32 s40, 12
	s_cselect_b32 s86, s9, s10
	s_cselect_b32 s87, s5, s11
	s_cselect_b32 s84, s23, s30
	s_cselect_b32 s85, s22, s37
	s_add_u32 s10, s86, 0x8000
	s_addc_u32 s11, s87, 0
	ds_read_b128 v[16:19], v246
	ds_read_b128 v[20:23], v246 offset:1024
	ds_read_b128 v[24:27], v246 offset:2048
	ds_read_b128 v[32:35], v246 offset:3072
	ds_read_b128 v[48:51], v246 offset:16384
	ds_read_b128 v[52:55], v246 offset:17408
	ds_read_b128 v[56:59], v246 offset:18432
	ds_read_b128 v[60:63], v246 offset:19456
	s_add_i32 m0, s33, 0xc000
	ds_read_b128 v[160:163], v193
	ds_read_b128 v[164:167], v193 offset:1024
	ds_read_b128 v[180:183], v193 offset:2048
	ds_read_b128 v[184:187], v193 offset:3072
	ds_read_b128 v[188:191], v193 offset:4096
	ds_read_b128 v[194:197], v193 offset:5120
	ds_read_b128 v[198:201], v193 offset:6144
	ds_read_b128 v[202:205], v193 offset:7168
	global_load_lds_dwordx4 v176, s[6:7]
	s_add_i32 m0, s33, 0xe000
	s_nop 0
	global_load_lds_dwordx4 v178, s[6:7]
	s_waitcnt vmcnt(8) lgkmcnt(0)
	s_barrier
	v_mfma_f32_16x16x32_bf16 v[156:159], v[16:19], v[160:163], 0
	v_mfma_f32_16x16x32_bf16 v[152:155], v[24:27], v[160:163], 0
	v_mfma_f32_16x16x32_bf16 v[140:143], v[16:19], v[180:183], 0
	v_mfma_f32_16x16x32_bf16 v[136:139], v[24:27], v[180:183], 0
	v_mfma_f32_16x16x32_bf16 v[124:127], v[16:19], v[188:191], 0
	v_mfma_f32_16x16x32_bf16 v[120:123], v[24:27], v[188:191], 0
	v_mfma_f32_16x16x32_bf16 v[108:111], v[16:19], v[198:201], 0
	v_mfma_f32_16x16x32_bf16 v[104:107], v[24:27], v[198:201], 0
	v_mfma_f32_16x16x32_bf16 v[156:159], v[20:23], v[164:167], v[156:159]
	v_mfma_f32_16x16x32_bf16 v[152:155], v[32:35], v[164:167], v[152:155]
	v_mfma_f32_16x16x32_bf16 v[140:143], v[20:23], v[184:187], v[140:143]
	v_mfma_f32_16x16x32_bf16 v[136:139], v[32:35], v[184:187], v[136:139]
	v_mfma_f32_16x16x32_bf16 v[124:127], v[20:23], v[194:197], v[124:127]
	v_mfma_f32_16x16x32_bf16 v[120:123], v[32:35], v[194:197], v[120:123]
	v_mfma_f32_16x16x32_bf16 v[108:111], v[20:23], v[202:205], v[108:111]
	v_mfma_f32_16x16x32_bf16 v[104:107], v[32:35], v[202:205], v[104:107]
	v_mfma_f32_16x16x32_bf16 v[148:151], v[48:51], v[160:163], 0
	v_mfma_f32_16x16x32_bf16 v[144:147], v[56:59], v[160:163], 0
	v_mfma_f32_16x16x32_bf16 v[132:135], v[48:51], v[180:183], 0
	v_mfma_f32_16x16x32_bf16 v[128:131], v[56:59], v[180:183], 0
	v_mfma_f32_16x16x32_bf16 v[116:119], v[48:51], v[188:191], 0
	v_mfma_f32_16x16x32_bf16 v[112:115], v[56:59], v[188:191], 0
	v_mfma_f32_16x16x32_bf16 v[100:103], v[48:51], v[198:201], 0
	v_mfma_f32_16x16x32_bf16 v[96:99], v[56:59], v[198:201], 0
	v_mfma_f32_16x16x32_bf16 v[148:151], v[52:55], v[164:167], v[148:151]
	v_mfma_f32_16x16x32_bf16 v[144:147], v[60:63], v[164:167], v[144:147]
	v_mfma_f32_16x16x32_bf16 v[132:135], v[52:55], v[184:187], v[132:135]
	v_mfma_f32_16x16x32_bf16 v[128:131], v[60:63], v[184:187], v[128:131]
	v_mfma_f32_16x16x32_bf16 v[116:119], v[52:55], v[194:197], v[116:119]
	v_mfma_f32_16x16x32_bf16 v[112:115], v[60:63], v[194:197], v[112:115]
	v_mfma_f32_16x16x32_bf16 v[100:103], v[52:55], v[202:205], v[100:103]
	v_mfma_f32_16x16x32_bf16 v[96:99], v[60:63], v[202:205], v[96:99]
	s_barrier
	s_add_i32 m0, s57, 0x10000
	ds_read_b128 v[160:163], v193 offset:16384
	ds_read_b128 v[164:167], v193 offset:17408
	ds_read_b128 v[180:183], v193 offset:18432
	ds_read_b128 v[184:187], v193 offset:19456
	ds_read_b128 v[188:191], v193 offset:20480
	ds_read_b128 v[194:197], v193 offset:21504
	ds_read_b128 v[198:201], v193 offset:22528
	ds_read_b128 v[202:205], v193 offset:23552
	global_load_lds_dwordx4 v170, s[84:85]
	s_add_i32 m0, s57, 0x12000
	s_add_u32 s88, s84, 0x4000
	s_addc_u32 s89, s85, 0
	global_load_lds_dwordx4 v174, s[84:85]
	s_add_i32 m0, s57, 0x14000
	s_nop 0
	global_load_lds_dwordx4 v170, s[88:89]
	s_add_i32 m0, s57, 0x16000
	s_nop 0
	global_load_lds_dwordx4 v174, s[88:89]
	s_mov_b32 m0, s33
	s_nop 0
	global_load_lds_dwordx4 v168, s[86:87]
	s_mov_b32 m0, s42
	s_nop 0
	global_load_lds_dwordx4 v172, s[86:87]
	s_waitcnt vmcnt(8) lgkmcnt(0)
	s_barrier
; #define PG8_STAGE(bufoff, gbase, voff) do { _Pragma("unroll") for (int _i = 0; _i < 2; ++_i) \
;         __builtin_amdgcn_global_load_lds((const unsigned*)((const char*)(gbase) + (voff)[_i]), (PG8_LAS unsigned*)(lds + (bufoff) + ldsw + _i * 8192), 16, 0, 0); } while (0)
; #define PG8_LDA(dst, b, h) do { _Pragma("unroll") for (int m = 0; m < 4; ++m) _Pragma("unroll") for (int k = 0; k < 2; ++k) dst[m][k] = *(const PG8_LAS bf16x8*)(lds + PG8_SA(b, h) + aoff + m * 2048 + k * 1024); } while (0)
; #define PG8_LDB(dst, b, h) do { _Pragma("unroll") for (int n = 0; n < 2; ++n) _Pragma("unroll") for (int k = 0; k < 2; ++k) dst[n][k] = *(const PG8_LAS bf16x8*)(lds + PG8_SB(b, h) + boff + n * 2048 + k * 1024); } while (0)
; #define PG8_MMA(ai, bj, At, Bt) do { __builtin_amdgcn_s_setprio(1); _Pragma("unroll") for (int m = 0; m < 4; ++m) _Pragma("unroll") for (int n = 0; n < 2; ++n) _Pragma("unroll") for (int k = 0; k < 2; ++k) \
;         acc[ai][bj][m][n] = __builtin_amdgcn_mfma_f32_16x16x32_bf16(Bt[n][k], At[m][k], acc[ai][bj][m][n], 0, 0, 0); __builtin_amdgcn_s_setprio(0); } while (0)
; #define PG8_WAIT_V(n) asm volatile("s_waitcnt vmcnt(" #n ")" ::: "memory")
; #define PG8_WAIT_L(n) asm volatile("s_waitcnt lgkmcnt(" #n ")" ::: "memory")
; #define PG8_BAR __builtin_amdgcn_s_barrier()
; #define PG8_SCHED __builtin_amdgcn_sched_barrier(0)
; template <class Epi, class Sched, bool ALIGN_EPI = false, bool SP2 = false>
; __device__ __forceinline__ void gemm_phase(PG8_LAS unsigned char* lds, const Gemm g, const Sched& S, const Epi& E) {
;     ...
;             PG8_WAIT_V(8); PG8_WAIT_L(0); PG8_BAR; PG8_MMA(0, 0, At, B0); PG8_MMA(0, 1, At, B1); PG8_BAR; PG8_SCHED;
;             PG8_LDA(At, 0, 1); PG8_STAGE(PG8_SB(0, 0), b2, voffB); PG8_STAGE(PG8_SB(0, 1), b2 + hstep, voffB); PG8_STAGE(PG8_SA(0, 0), a2, voffA);
;             PG8_WAIT_V(8); PG8_WAIT_L(0); PG8_BAR; PG8_MMA(1, 0, At, B0); PG8_MMA(1, 1, At, B1); PG8_BAR; PG8_SCHED;
;             PG8_LDB(B0, 1, 0); PG8_LDB(B1, 1, 1); PG8_SCHED; PG8_LDA(At, 1, 0); PG8_STAGE(PG8_SA(0, 1), a2 + hstep, voffA);
;             PG8_WAIT_V(8); PG8_WAIT_L(0); PG8_BAR; PG8_MMA(0, 0, At, B0); PG8_MMA(0, 1, At, B1); PG8_BAR; PG8_SCHED;
	v_mfma_f32_16x16x32_bf16 v[92:95], v[16:19], v[160:163], 0
	v_mfma_f32_16x16x32_bf16 v[88:91], v[24:27], v[160:163], 0
	v_mfma_f32_16x16x32_bf16 v[76:79], v[16:19], v[180:183], 0
	v_mfma_f32_16x16x32_bf16 v[72:75], v[24:27], v[180:183], 0
	v_mfma_f32_16x16x32_bf16 v[44:47], v[16:19], v[188:191], 0
	v_mfma_f32_16x16x32_bf16 v[40:43], v[24:27], v[188:191], 0
	v_mfma_f32_16x16x32_bf16 v[12:15], v[16:19], v[198:201], 0
	v_mfma_f32_16x16x32_bf16 v[8:11], v[24:27], v[198:201], 0
	v_mfma_f32_16x16x32_bf16 v[92:95], v[20:23], v[164:167], v[92:95]
	v_mfma_f32_16x16x32_bf16 v[88:91], v[32:35], v[164:167], v[88:91]
	v_mfma_f32_16x16x32_bf16 v[76:79], v[20:23], v[184:187], v[76:79]
	v_mfma_f32_16x16x32_bf16 v[72:75], v[32:35], v[184:187], v[72:75]
	v_mfma_f32_16x16x32_bf16 v[44:47], v[20:23], v[194:197], v[44:47]
	v_mfma_f32_16x16x32_bf16 v[40:43], v[32:35], v[194:197], v[40:43]
	v_mfma_f32_16x16x32_bf16 v[12:15], v[20:23], v[202:205], v[12:15]
	v_mfma_f32_16x16x32_bf16 v[8:11], v[32:35], v[202:205], v[8:11]
	v_mfma_f32_16x16x32_bf16 v[36:39], v[48:51], v[188:191], 0
	v_mfma_f32_16x16x32_bf16 v[28:31], v[56:59], v[188:191], 0
	v_mfma_f32_16x16x32_bf16 v[4:7], v[48:51], v[198:201], 0
	v_mfma_f32_16x16x32_bf16 v[0:3], v[56:59], v[198:201], 0
	v_mfma_f32_16x16x32_bf16 v[16:19], v[48:51], v[160:163], 0
	v_mfma_f32_16x16x32_bf16 v[20:23], v[56:59], v[160:163], 0
	v_mfma_f32_16x16x32_bf16 v[24:27], v[48:51], v[180:183], 0
	v_mfma_f32_16x16x32_bf16 v[32:35], v[56:59], v[180:183], 0
	v_mfma_f32_16x16x32_bf16 v[36:39], v[52:55], v[194:197], v[36:39]
	v_mfma_f32_16x16x32_bf16 v[28:31], v[60:63], v[194:197], v[28:31]
	v_mfma_f32_16x16x32_bf16 v[4:7], v[52:55], v[202:205], v[4:7]
	v_mfma_f32_16x16x32_bf16 v[0:3], v[60:63], v[202:205], v[0:3]
	v_mfma_f32_16x16x32_bf16 v[16:19], v[52:55], v[164:167], v[16:19]
	v_mfma_f32_16x16x32_bf16 v[20:23], v[60:63], v[164:167], v[20:23]
	v_mfma_f32_16x16x32_bf16 v[24:27], v[52:55], v[184:187], v[24:27]
	v_mfma_f32_16x16x32_bf16 v[32:35], v[60:63], v[184:187], v[32:35]
	s_barrier
	ds_read_b128 v[48:51], v246 offset:32768
	ds_read_b128 v[52:55], v246 offset:33792
	ds_read_b128 v[56:59], v246 offset:34816
	ds_read_b128 v[60:63], v246 offset:35840
	ds_read_b128 v[160:163], v246 offset:49152
	ds_read_b128 v[164:167], v246 offset:50176
	ds_read_b128 v[180:183], v246 offset:51200
	ds_read_b128 v[184:187], v246 offset:52224
	s_add_u32 s86, s86, 0x4000
	s_addc_u32 s87, s87, 0
	s_mov_b32 m0, s64
	ds_read_b128 v[64:67], v193 offset:32768
	ds_read_b128 v[68:71], v193 offset:33792
	ds_read_b128 v[80:83], v193 offset:34816
	ds_read_b128 v[84:87], v193 offset:35840
	ds_read_b128 v[188:191], v193 offset:36864
	ds_read_b128 v[194:197], v193 offset:37888
	ds_read_b128 v[198:201], v193 offset:38912
	ds_read_b128 v[202:205], v193 offset:39936
	global_load_lds_dwordx4 v168, s[86:87]
	s_mov_b32 m0, s65
	s_nop 0
	global_load_lds_dwordx4 v172, s[86:87]
	s_waitcnt vmcnt(8) lgkmcnt(0)
	s_barrier
	v_mfma_f32_16x16x32_bf16 v[156:159], v[48:51], v[64:67], v[156:159]
	v_mfma_f32_16x16x32_bf16 v[152:155], v[56:59], v[64:67], v[152:155]
	v_mfma_f32_16x16x32_bf16 v[140:143], v[48:51], v[80:83], v[140:143]
	v_mfma_f32_16x16x32_bf16 v[136:139], v[56:59], v[80:83], v[136:139]
	v_mfma_f32_16x16x32_bf16 v[124:127], v[48:51], v[188:191], v[124:127]
	v_mfma_f32_16x16x32_bf16 v[120:123], v[56:59], v[188:191], v[120:123]
	v_mfma_f32_16x16x32_bf16 v[108:111], v[48:51], v[198:201], v[108:111]
	v_mfma_f32_16x16x32_bf16 v[104:107], v[56:59], v[198:201], v[104:107]
	v_mfma_f32_16x16x32_bf16 v[156:159], v[52:55], v[68:71], v[156:159]
	v_mfma_f32_16x16x32_bf16 v[152:155], v[60:63], v[68:71], v[152:155]
	v_mfma_f32_16x16x32_bf16 v[140:143], v[52:55], v[84:87], v[140:143]
	v_mfma_f32_16x16x32_bf16 v[136:139], v[60:63], v[84:87], v[136:139]
	v_mfma_f32_16x16x32_bf16 v[124:127], v[52:55], v[194:197], v[124:127]
	v_mfma_f32_16x16x32_bf16 v[120:123], v[60:63], v[194:197], v[120:123]
	v_mfma_f32_16x16x32_bf16 v[108:111], v[52:55], v[202:205], v[108:111]
	v_mfma_f32_16x16x32_bf16 v[104:107], v[60:63], v[202:205], v[104:107]
	v_mfma_f32_16x16x32_bf16 v[148:151], v[160:163], v[64:67], v[148:151]
	v_mfma_f32_16x16x32_bf16 v[64:67], v[180:183], v[64:67], v[144:147]
	v_mfma_f32_16x16x32_bf16 v[144:147], v[184:187], v[68:71], v[64:67]
	v_mfma_f32_16x16x32_bf16 v[64:67], v[160:163], v[80:83], v[132:135]
	v_mfma_f32_16x16x32_bf16 v[132:135], v[164:167], v[84:87], v[64:67]
	v_mfma_f32_16x16x32_bf16 v[64:67], v[180:183], v[80:83], v[128:131]
	v_mfma_f32_16x16x32_bf16 v[128:131], v[184:187], v[84:87], v[64:67]
	v_mfma_f32_16x16x32_bf16 v[64:67], v[160:163], v[188:191], v[116:119]
	v_mfma_f32_16x16x32_bf16 v[116:119], v[164:167], v[194:197], v[64:67]
	v_mfma_f32_16x16x32_bf16 v[64:67], v[180:183], v[188:191], v[112:115]
	v_mfma_f32_16x16x32_bf16 v[112:115], v[184:187], v[194:197], v[64:67]
	v_mfma_f32_16x16x32_bf16 v[64:67], v[160:163], v[198:201], v[100:103]
	v_mfma_f32_16x16x32_bf16 v[100:103], v[164:167], v[202:205], v[64:67]
	v_mfma_f32_16x16x32_bf16 v[64:67], v[180:183], v[198:201], v[96:99]
	v_mfma_f32_16x16x32_bf16 v[148:151], v[164:167], v[68:71], v[148:151]
	v_mfma_f32_16x16x32_bf16 v[96:99], v[184:187], v[202:205], v[64:67]
	s_barrier
; #define PG8_STAGE(bufoff, gbase, voff) do { _Pragma("unroll") for (int _i = 0; _i < 2; ++_i) \
;         __builtin_amdgcn_global_load_lds((const unsigned*)((const char*)(gbase) + (voff)[_i]), (PG8_LAS unsigned*)(lds + (bufoff) + ldsw + _i * 8192), 16, 0, 0); } while (0)
; #define PG8_LDA(dst, b, h) do { _Pragma("unroll") for (int m = 0; m < 4; ++m) _Pragma("unroll") for (int k = 0; k < 2; ++k) dst[m][k] = *(const PG8_LAS bf16x8*)(lds + PG8_SA(b, h) + aoff + m * 2048 + k * 1024); } while (0)
; #define PG8_LDB(dst, b, h) do { _Pragma("unroll") for (int n = 0; n < 2; ++n) _Pragma("unroll") for (int k = 0; k < 2; ++k) dst[n][k] = *(const PG8_LAS bf16x8*)(lds + PG8_SB(b, h) + boff + n * 2048 + k * 1024); } while (0)
; template <class Epi, class Sched, bool ALIGN_EPI = false, bool SP2 = false>
; __device__ __forceinline__ void gemm_phase(PG8_LAS unsigned char* lds, const Gemm g, const Sched& S, const Epi& E) {
;     ...
;         for (int t = 0; t < nt; t += 2) {
;             const bool last = (t == nt - 2);
;             const char* a1 = cA + (size_t)(t + 1) * kstep;
;             const char* a2 = last ? nA : cA + (size_t)(t + 2) * kstep; const char* b2 = last ? nB : cB + (size_t)(t + 2) * kstep;
;             const char* a3 = a2 + kstep; const char* b3 = b2 + kstep;
;             if (last && has_next) S.a_ready(nxt);
;             if constexpr (SP2) {
;             PG8_LDB(B0, 0, 0); PG8_LDB(B1, 0, 1); PG8_SCHED; PG8_LDA(At, 0, 0); PG8_STAGE(PG8_SA(1, 1), a1 + hstep, voffA);
;             PG8_WAIT_V(8); PG8_WAIT_L(0); PG8_BAR; PG8_MMA(0, 0, At, B0); PG8_MMA(0, 1, At, B1); PG8_BAR; PG8_SCHED;
;             PG8_LDA(At, 0, 1); PG8_STAGE(PG8_SB(0, 0), b2, voffB); PG8_STAGE(PG8_SB(0, 1), b2 + hstep, voffB); PG8_STAGE(PG8_SA(0, 0), a2, voffA);
;             PG8_WAIT_V(8); PG8_WAIT_L(0); PG8_BAR; PG8_MMA(1, 0, At, B0); PG8_MMA(1, 1, At, B1); PG8_BAR; PG8_SCHED;
;             PG8_LDB(B0, 1, 0); PG8_LDB(B1, 1, 1); PG8_SCHED; PG8_LDA(At, 1, 0); PG8_STAGE(PG8_SA(0, 1), a2 + hstep, voffA);
;             PG8_WAIT_V(8); PG8_WAIT_L(0); PG8_BAR; PG8_MMA(0, 0, At, B0); PG8_MMA(0, 1, At, B1); PG8_BAR; PG8_SCHED;
;             PG8_LDA(At, 1, 1); PG8_STAGE(PG8_SB(1, 0), b3, voffB); PG8_STAGE(PG8_SB(1, 1), b3 + hstep, voffB); PG8_STAGE(PG8_SA(1, 0), a3, voffA);
;             PG8_WAIT_V(8); PG8_WAIT_L(0); PG8_BAR; PG8_MMA(1, 0, At, B0); PG8_MMA(1, 1, At, B1); PG8_BAR; PG8_SCHED;
	s_add_u32 s86, s84, 0x8000
	s_addc_u32 s87, s85, 0
	s_add_i32 m0, s57, 0x18000
	ds_read_b128 v[64:67], v193 offset:49152
	ds_read_b128 v[68:71], v193 offset:50176
	ds_read_b128 v[188:191], v193 offset:51200
	ds_read_b128 v[194:197], v193 offset:52224
	ds_read_b128 v[198:201], v193 offset:53248
	ds_read_b128 v[202:205], v193 offset:54272
	ds_read_b128 v[206:209], v193 offset:55296
	ds_read_b128 v[210:213], v193 offset:56320
	global_load_lds_dwordx4 v170, s[86:87]
	s_add_i32 m0, s57, 0x1a000
	s_add_u32 s84, s84, 0xc000
	s_addc_u32 s85, s85, 0
	global_load_lds_dwordx4 v174, s[86:87]
	s_add_i32 m0, s57, 0x1c000
	s_nop 0
	global_load_lds_dwordx4 v170, s[84:85]
	s_add_i32 m0, s57, 0x1e000
	s_nop 0
	global_load_lds_dwordx4 v174, s[84:85]
	s_mov_b32 m0, s53
	s_nop 0
	global_load_lds_dwordx4 v168, s[10:11]
	s_mov_b32 m0, s27
	s_nop 0
	global_load_lds_dwordx4 v172, s[10:11]
	s_waitcnt vmcnt(8) lgkmcnt(0)
	s_barrier
	v_mfma_f32_16x16x32_bf16 v[80:83], v[48:51], v[64:67], v[92:95]
	v_mfma_f32_16x16x32_bf16 v[92:95], v[52:55], v[68:71], v[80:83]
	v_mfma_f32_16x16x32_bf16 v[80:83], v[56:59], v[64:67], v[88:91]
	v_mfma_f32_16x16x32_bf16 v[76:79], v[48:51], v[188:191], v[76:79]
	v_mfma_f32_16x16x32_bf16 v[72:75], v[56:59], v[188:191], v[72:75]
	v_mfma_f32_16x16x32_bf16 v[44:47], v[48:51], v[198:201], v[44:47]
	v_mfma_f32_16x16x32_bf16 v[40:43], v[56:59], v[198:201], v[40:43]
	v_mfma_f32_16x16x32_bf16 v[12:15], v[48:51], v[206:209], v[12:15]
	v_mfma_f32_16x16x32_bf16 v[8:11], v[56:59], v[206:209], v[8:11]
	v_mfma_f32_16x16x32_bf16 v[88:91], v[60:63], v[68:71], v[80:83]
	v_mfma_f32_16x16x32_bf16 v[76:79], v[52:55], v[194:197], v[76:79]
	v_mfma_f32_16x16x32_bf16 v[72:75], v[60:63], v[194:197], v[72:75]
	v_mfma_f32_16x16x32_bf16 v[44:47], v[52:55], v[202:205], v[44:47]
	v_mfma_f32_16x16x32_bf16 v[40:43], v[60:63], v[202:205], v[40:43]
	v_mfma_f32_16x16x32_bf16 v[12:15], v[52:55], v[210:213], v[12:15]
	v_mfma_f32_16x16x32_bf16 v[8:11], v[60:63], v[210:213], v[8:11]
	v_mfma_f32_16x16x32_bf16 v[16:19], v[160:163], v[64:67], v[16:19]
	v_mfma_f32_16x16x32_bf16 v[84:87], v[164:167], v[68:71], v[16:19]
	v_mfma_f32_16x16x32_bf16 v[16:19], v[180:183], v[64:67], v[20:23]
	v_mfma_f32_16x16x32_bf16 v[80:83], v[184:187], v[68:71], v[16:19]
	v_mfma_f32_16x16x32_bf16 v[16:19], v[160:163], v[188:191], v[24:27]
	v_mfma_f32_16x16x32_bf16 v[68:71], v[164:167], v[194:197], v[16:19]
	v_mfma_f32_16x16x32_bf16 v[16:19], v[180:183], v[188:191], v[32:35]
	v_mfma_f32_16x16x32_bf16 v[64:67], v[184:187], v[194:197], v[16:19]
	v_mfma_f32_16x16x32_bf16 v[16:19], v[160:163], v[198:201], v[36:39]
	v_mfma_f32_16x16x32_bf16 v[36:39], v[164:167], v[202:205], v[16:19]
	v_mfma_f32_16x16x32_bf16 v[16:19], v[180:183], v[198:201], v[28:31]
	v_mfma_f32_16x16x32_bf16 v[4:7], v[160:163], v[206:209], v[4:7]
	v_mfma_f32_16x16x32_bf16 v[0:3], v[180:183], v[206:209], v[0:3]
	v_mfma_f32_16x16x32_bf16 v[28:31], v[184:187], v[202:205], v[16:19]
	v_mfma_f32_16x16x32_bf16 v[4:7], v[164:167], v[210:213], v[4:7]
	v_mfma_f32_16x16x32_bf16 v[0:3], v[184:187], v[210:213], v[0:3]
	s_barrier
	s_add_i32 s40, s40, 2
	s_add_u32 s6, s6, 0x10000
	s_addc_u32 s7, s7, 0
	s_add_u32 s30, s30, 0x10000
	s_addc_u32 s37, s37, 0
	s_cmp_gt_u32 s40, 13
.LBB0_1130:
	s_add_u32 s10, s6, 0x4000
	s_addc_u32 s11, s7, 0
	s_cmp_eq_u32 s40, 12
	s_cselect_b32 s86, s9, s10
	s_cselect_b32 s87, s5, s11
	s_cselect_b32 s84, s23, s30
	s_cselect_b32 s85, s22, s37
	s_add_u32 s10, s86, 0x8000
	s_addc_u32 s11, s87, 0
	ds_read_b128 v[16:19], v246
	ds_read_b128 v[20:23], v246 offset:1024
	ds_read_b128 v[24:27], v246 offset:2048
	ds_read_b128 v[32:35], v246 offset:3072
	ds_read_b128 v[48:51], v246 offset:16384
	ds_read_b128 v[52:55], v246 offset:17408
	ds_read_b128 v[56:59], v246 offset:18432
	ds_read_b128 v[60:63], v246 offset:19456
	s_add_i32 m0, s33, 0xc000
	ds_read_b128 v[160:163], v193
	ds_read_b128 v[164:167], v193 offset:1024
	ds_read_b128 v[180:183], v193 offset:2048
	ds_read_b128 v[184:187], v193 offset:3072
	ds_read_b128 v[188:191], v193 offset:4096
	ds_read_b128 v[194:197], v193 offset:5120
	ds_read_b128 v[198:201], v193 offset:6144
	ds_read_b128 v[202:205], v193 offset:7168
	global_load_lds_dwordx4 v176, s[6:7]
	s_add_i32 m0, s33, 0xe000
	s_nop 0
	global_load_lds_dwordx4 v178, s[6:7]
	s_waitcnt vmcnt(8) lgkmcnt(0)
	s_barrier
	v_mfma_f32_16x16x32_bf16 v[156:159], v[16:19], v[160:163], v[156:159]
	v_mfma_f32_16x16x32_bf16 v[152:155], v[24:27], v[160:163], v[152:155]
	v_mfma_f32_16x16x32_bf16 v[140:143], v[16:19], v[180:183], v[140:143]
	v_mfma_f32_16x16x32_bf16 v[136:139], v[24:27], v[180:183], v[136:139]
	v_mfma_f32_16x16x32_bf16 v[124:127], v[16:19], v[188:191], v[124:127]
	v_mfma_f32_16x16x32_bf16 v[120:123], v[24:27], v[188:191], v[120:123]
	v_mfma_f32_16x16x32_bf16 v[108:111], v[16:19], v[198:201], v[108:111]
	v_mfma_f32_16x16x32_bf16 v[104:107], v[24:27], v[198:201], v[104:107]
	v_mfma_f32_16x16x32_bf16 v[156:159], v[20:23], v[164:167], v[156:159]
	v_mfma_f32_16x16x32_bf16 v[152:155], v[32:35], v[164:167], v[152:155]
	v_mfma_f32_16x16x32_bf16 v[140:143], v[20:23], v[184:187], v[140:143]
	v_mfma_f32_16x16x32_bf16 v[136:139], v[32:35], v[184:187], v[136:139]
	v_mfma_f32_16x16x32_bf16 v[124:127], v[20:23], v[194:197], v[124:127]
	v_mfma_f32_16x16x32_bf16 v[120:123], v[32:35], v[194:197], v[120:123]
	v_mfma_f32_16x16x32_bf16 v[108:111], v[20:23], v[202:205], v[108:111]
	v_mfma_f32_16x16x32_bf16 v[104:107], v[32:35], v[202:205], v[104:107]
	v_mfma_f32_16x16x32_bf16 v[148:151], v[48:51], v[160:163], v[148:151]
	v_mfma_f32_16x16x32_bf16 v[144:147], v[56:59], v[160:163], v[144:147]
	v_mfma_f32_16x16x32_bf16 v[132:135], v[48:51], v[180:183], v[132:135]
	v_mfma_f32_16x16x32_bf16 v[128:131], v[56:59], v[180:183], v[128:131]
	v_mfma_f32_16x16x32_bf16 v[116:119], v[48:51], v[188:191], v[116:119]
	v_mfma_f32_16x16x32_bf16 v[112:115], v[56:59], v[188:191], v[112:115]
	v_mfma_f32_16x16x32_bf16 v[100:103], v[48:51], v[198:201], v[100:103]
	v_mfma_f32_16x16x32_bf16 v[96:99], v[56:59], v[198:201], v[96:99]
	v_mfma_f32_16x16x32_bf16 v[148:151], v[52:55], v[164:167], v[148:151]
	v_mfma_f32_16x16x32_bf16 v[144:147], v[60:63], v[164:167], v[144:147]
	v_mfma_f32_16x16x32_bf16 v[132:135], v[52:55], v[184:187], v[132:135]
	v_mfma_f32_16x16x32_bf16 v[128:131], v[60:63], v[184:187], v[128:131]
	v_mfma_f32_16x16x32_bf16 v[116:119], v[52:55], v[194:197], v[116:119]
	v_mfma_f32_16x16x32_bf16 v[112:115], v[60:63], v[194:197], v[112:115]
	v_mfma_f32_16x16x32_bf16 v[100:103], v[52:55], v[202:205], v[100:103]
	v_mfma_f32_16x16x32_bf16 v[96:99], v[60:63], v[202:205], v[96:99]
	s_barrier
; #define PG8_STAGE(bufoff, gbase, voff) do { _Pragma("unroll") for (int _i = 0; _i < 2; ++_i) \
;         __builtin_amdgcn_global_load_lds((const unsigned*)((const char*)(gbase) + (voff)[_i]), (PG8_LAS unsigned*)(lds + (bufoff) + ldsw + _i * 8192), 16, 0, 0); } while (0)
; #define PG8_LDA(dst, b, h) do { _Pragma("unroll") for (int m = 0; m < 4; ++m) _Pragma("unroll") for (int k = 0; k < 2; ++k) dst[m][k] = *(const PG8_LAS bf16x8*)(lds + PG8_SA(b, h) + aoff + m * 2048 + k * 1024); } while (0)
; #define PG8_LDB(dst, b, h) do { _Pragma("unroll") for (int n = 0; n < 2; ++n) _Pragma("unroll") for (int k = 0; k < 2; ++k) dst[n][k] = *(const PG8_LAS bf16x8*)(lds + PG8_SB(b, h) + boff + n * 2048 + k * 1024); } while (0)
; #define PG8_MMA(ai, bj, At, Bt) do { __builtin_amdgcn_s_setprio(1); _Pragma("unroll") for (int m = 0; m < 4; ++m) _Pragma("unroll") for (int n = 0; n < 2; ++n) _Pragma("unroll") for (int k = 0; k < 2; ++k) \
;         acc[ai][bj][m][n] = __builtin_amdgcn_mfma_f32_16x16x32_bf16(Bt[n][k], At[m][k], acc[ai][bj][m][n], 0, 0, 0); __builtin_amdgcn_s_setprio(0); } while (0)
; #define PG8_WAIT_V(n) asm volatile("s_waitcnt vmcnt(" #n ")" ::: "memory")
; #define PG8_WAIT_L(n) asm volatile("s_waitcnt lgkmcnt(" #n ")" ::: "memory")
; #define PG8_BAR __builtin_amdgcn_s_barrier()
; #define PG8_SCHED __builtin_amdgcn_sched_barrier(0)
; template <class Epi, class Sched, bool ALIGN_EPI = false, bool SP2 = false>
; __device__ __forceinline__ void gemm_phase(PG8_LAS unsigned char* lds, const Gemm g, const Sched& S, const Epi& E) {
;     ...
;             PG8_WAIT_V(8); PG8_WAIT_L(0); PG8_BAR; PG8_MMA(0, 0, At, B0); PG8_MMA(0, 1, At, B1); PG8_BAR; PG8_SCHED;
;             PG8_LDA(At, 0, 1); PG8_STAGE(PG8_SB(0, 0), b2, voffB); PG8_STAGE(PG8_SB(0, 1), b2 + hstep, voffB); PG8_STAGE(PG8_SA(0, 0), a2, voffA);
;             PG8_WAIT_V(8); PG8_WAIT_L(0); PG8_BAR; PG8_MMA(1, 0, At, B0); PG8_MMA(1, 1, At, B1); PG8_BAR; PG8_SCHED;
;             PG8_LDB(B0, 1, 0); PG8_LDB(B1, 1, 1); PG8_SCHED; PG8_LDA(At, 1, 0); PG8_STAGE(PG8_SA(0, 1), a2 + hstep, voffA);
	s_add_i32 m0, s57, 0x10000
	ds_read_b128 v[160:163], v193 offset:16384
	ds_read_b128 v[164:167], v193 offset:17408
	ds_read_b128 v[180:183], v193 offset:18432
	ds_read_b128 v[184:187], v193 offset:19456
	ds_read_b128 v[188:191], v193 offset:20480
	ds_read_b128 v[194:197], v193 offset:21504
	ds_read_b128 v[198:201], v193 offset:22528
	ds_read_b128 v[202:205], v193 offset:23552
	global_load_lds_dwordx4 v170, s[84:85]
	s_add_i32 m0, s57, 0x12000
	s_add_u32 s88, s84, 0x4000
	s_addc_u32 s89, s85, 0
	global_load_lds_dwordx4 v174, s[84:85]
	s_add_i32 m0, s57, 0x14000
	s_nop 0
	global_load_lds_dwordx4 v170, s[88:89]
	s_add_i32 m0, s57, 0x16000
	s_nop 0
	global_load_lds_dwordx4 v174, s[88:89]
	s_mov_b32 m0, s33
	s_nop 0
	global_load_lds_dwordx4 v168, s[86:87]
	s_mov_b32 m0, s42
	s_nop 0
	global_load_lds_dwordx4 v172, s[86:87]
	s_waitcnt vmcnt(8) lgkmcnt(0)
	s_barrier
	v_mfma_f32_16x16x32_bf16 v[92:95], v[16:19], v[160:163], v[92:95]
	v_mfma_f32_16x16x32_bf16 v[88:91], v[24:27], v[160:163], v[88:91]
	v_mfma_f32_16x16x32_bf16 v[76:79], v[16:19], v[180:183], v[76:79]
	v_mfma_f32_16x16x32_bf16 v[72:75], v[24:27], v[180:183], v[72:75]
	v_mfma_f32_16x16x32_bf16 v[44:47], v[16:19], v[188:191], v[44:47]
	v_mfma_f32_16x16x32_bf16 v[40:43], v[24:27], v[188:191], v[40:43]
	v_mfma_f32_16x16x32_bf16 v[12:15], v[16:19], v[198:201], v[12:15]
	v_mfma_f32_16x16x32_bf16 v[8:11], v[24:27], v[198:201], v[8:11]
	v_mfma_f32_16x16x32_bf16 v[92:95], v[20:23], v[164:167], v[92:95]
	v_mfma_f32_16x16x32_bf16 v[88:91], v[32:35], v[164:167], v[88:91]
	v_mfma_f32_16x16x32_bf16 v[76:79], v[20:23], v[184:187], v[76:79]
	v_mfma_f32_16x16x32_bf16 v[72:75], v[32:35], v[184:187], v[72:75]
	v_mfma_f32_16x16x32_bf16 v[44:47], v[20:23], v[194:197], v[44:47]
	v_mfma_f32_16x16x32_bf16 v[40:43], v[32:35], v[194:197], v[40:43]
	v_mfma_f32_16x16x32_bf16 v[12:15], v[20:23], v[202:205], v[12:15]
	v_mfma_f32_16x16x32_bf16 v[8:11], v[32:35], v[202:205], v[8:11]
	v_mfma_f32_16x16x32_bf16 v[36:39], v[48:51], v[188:191], v[36:39]
	v_mfma_f32_16x16x32_bf16 v[28:31], v[56:59], v[188:191], v[28:31]
	v_mfma_f32_16x16x32_bf16 v[4:7], v[48:51], v[198:201], v[4:7]
	v_mfma_f32_16x16x32_bf16 v[0:3], v[56:59], v[198:201], v[0:3]
	v_mfma_f32_16x16x32_bf16 v[16:19], v[48:51], v[160:163], v[84:87]
	v_mfma_f32_16x16x32_bf16 v[20:23], v[56:59], v[160:163], v[80:83]
	v_mfma_f32_16x16x32_bf16 v[24:27], v[48:51], v[180:183], v[68:71]
	v_mfma_f32_16x16x32_bf16 v[32:35], v[56:59], v[180:183], v[64:67]
	v_mfma_f32_16x16x32_bf16 v[36:39], v[52:55], v[194:197], v[36:39]
	v_mfma_f32_16x16x32_bf16 v[28:31], v[60:63], v[194:197], v[28:31]
	v_mfma_f32_16x16x32_bf16 v[4:7], v[52:55], v[202:205], v[4:7]
	v_mfma_f32_16x16x32_bf16 v[0:3], v[60:63], v[202:205], v[0:3]
	v_mfma_f32_16x16x32_bf16 v[16:19], v[52:55], v[164:167], v[16:19]
	v_mfma_f32_16x16x32_bf16 v[20:23], v[60:63], v[164:167], v[20:23]
	v_mfma_f32_16x16x32_bf16 v[24:27], v[52:55], v[184:187], v[24:27]
	v_mfma_f32_16x16x32_bf16 v[32:35], v[60:63], v[184:187], v[32:35]
	s_barrier
	ds_read_b128 v[48:51], v246 offset:32768
	ds_read_b128 v[52:55], v246 offset:33792
	ds_read_b128 v[56:59], v246 offset:34816
	ds_read_b128 v[60:63], v246 offset:35840
	ds_read_b128 v[160:163], v246 offset:49152
	ds_read_b128 v[164:167], v246 offset:50176
	ds_read_b128 v[180:183], v246 offset:51200
	ds_read_b128 v[184:187], v246 offset:52224
	s_add_u32 s86, s86, 0x4000
	s_addc_u32 s87, s87, 0
	s_mov_b32 m0, s64
	ds_read_b128 v[64:67], v193 offset:32768
	ds_read_b128 v[68:71], v193 offset:33792
	ds_read_b128 v[80:83], v193 offset:34816
	ds_read_b128 v[84:87], v193 offset:35840
	ds_read_b128 v[188:191], v193 offset:36864
	ds_read_b128 v[194:197], v193 offset:37888
	ds_read_b128 v[198:201], v193 offset:38912
	ds_read_b128 v[202:205], v193 offset:39936
	global_load_lds_dwordx4 v168, s[86:87]
	s_mov_b32 m0, s65
	s_nop 0
	global_load_lds_dwordx4 v172, s[86:87]
	s_waitcnt vmcnt(8) lgkmcnt(0)
	s_barrier
; #define PG8_STAGE(bufoff, gbase, voff) do { _Pragma("unroll") for (int _i = 0; _i < 2; ++_i) \
;         __builtin_amdgcn_global_load_lds((const unsigned*)((const char*)(gbase) + (voff)[_i]), (PG8_LAS unsigned*)(lds + (bufoff) + ldsw + _i * 8192), 16, 0, 0); } while (0)
; #define PG8_LDA(dst, b, h) do { _Pragma("unroll") for (int m = 0; m < 4; ++m) _Pragma("unroll") for (int k = 0; k < 2; ++k) dst[m][k] = *(const PG8_LAS bf16x8*)(lds + PG8_SA(b, h) + aoff + m * 2048 + k * 1024); } while (0)
; #define PG8_MMA(ai, bj, At, Bt) do { __builtin_amdgcn_s_setprio(1); _Pragma("unroll") for (int m = 0; m < 4; ++m) _Pragma("unroll") for (int n = 0; n < 2; ++n) _Pragma("unroll") for (int k = 0; k < 2; ++k) \
;         acc[ai][bj][m][n] = __builtin_amdgcn_mfma_f32_16x16x32_bf16(Bt[n][k], At[m][k], acc[ai][bj][m][n], 0, 0, 0); __builtin_amdgcn_s_setprio(0); } while (0)
; #define PG8_WAIT_V(n) asm volatile("s_waitcnt vmcnt(" #n ")" ::: "memory")
; #define PG8_WAIT_L(n) asm volatile("s_waitcnt lgkmcnt(" #n ")" ::: "memory")
; #define PG8_BAR __builtin_amdgcn_s_barrier()
; #define PG8_SCHED __builtin_amdgcn_sched_barrier(0)
; template <class Epi, class Sched, bool ALIGN_EPI = false, bool SP2 = false>
; __device__ __forceinline__ void gemm_phase(PG8_LAS unsigned char* lds, const Gemm g, const Sched& S, const Epi& E) {
;     ...
;             PG8_WAIT_V(8); PG8_WAIT_L(0); PG8_BAR; PG8_MMA(0, 0, At, B0); PG8_MMA(0, 1, At, B1); PG8_BAR; PG8_SCHED;
;             PG8_LDA(At, 1, 1); PG8_STAGE(PG8_SB(1, 0), b3, voffB); PG8_STAGE(PG8_SB(1, 1), b3 + hstep, voffB); PG8_STAGE(PG8_SA(1, 0), a3, voffA);
;             PG8_WAIT_V(8); PG8_WAIT_L(0); PG8_BAR; PG8_MMA(1, 0, At, B0); PG8_MMA(1, 1, At, B1); PG8_BAR; PG8_SCHED;
	v_mfma_f32_16x16x32_bf16 v[156:159], v[48:51], v[64:67], v[156:159]
	v_mfma_f32_16x16x32_bf16 v[152:155], v[56:59], v[64:67], v[152:155]
	v_mfma_f32_16x16x32_bf16 v[140:143], v[48:51], v[80:83], v[140:143]
	v_mfma_f32_16x16x32_bf16 v[136:139], v[56:59], v[80:83], v[136:139]
	v_mfma_f32_16x16x32_bf16 v[124:127], v[48:51], v[188:191], v[124:127]
	v_mfma_f32_16x16x32_bf16 v[120:123], v[56:59], v[188:191], v[120:123]
	v_mfma_f32_16x16x32_bf16 v[108:111], v[48:51], v[198:201], v[108:111]
	v_mfma_f32_16x16x32_bf16 v[104:107], v[56:59], v[198:201], v[104:107]
	v_mfma_f32_16x16x32_bf16 v[156:159], v[52:55], v[68:71], v[156:159]
	v_mfma_f32_16x16x32_bf16 v[152:155], v[60:63], v[68:71], v[152:155]
	v_mfma_f32_16x16x32_bf16 v[140:143], v[52:55], v[84:87], v[140:143]
	v_mfma_f32_16x16x32_bf16 v[136:139], v[60:63], v[84:87], v[136:139]
	v_mfma_f32_16x16x32_bf16 v[124:127], v[52:55], v[194:197], v[124:127]
	v_mfma_f32_16x16x32_bf16 v[120:123], v[60:63], v[194:197], v[120:123]
	v_mfma_f32_16x16x32_bf16 v[108:111], v[52:55], v[202:205], v[108:111]
	v_mfma_f32_16x16x32_bf16 v[104:107], v[60:63], v[202:205], v[104:107]
	v_mfma_f32_16x16x32_bf16 v[148:151], v[160:163], v[64:67], v[148:151]
	v_mfma_f32_16x16x32_bf16 v[64:67], v[180:183], v[64:67], v[144:147]
	v_mfma_f32_16x16x32_bf16 v[144:147], v[184:187], v[68:71], v[64:67]
	v_mfma_f32_16x16x32_bf16 v[64:67], v[160:163], v[80:83], v[132:135]
	v_mfma_f32_16x16x32_bf16 v[132:135], v[164:167], v[84:87], v[64:67]
	v_mfma_f32_16x16x32_bf16 v[64:67], v[180:183], v[80:83], v[128:131]
	v_mfma_f32_16x16x32_bf16 v[128:131], v[184:187], v[84:87], v[64:67]
	v_mfma_f32_16x16x32_bf16 v[64:67], v[160:163], v[188:191], v[116:119]
	v_mfma_f32_16x16x32_bf16 v[116:119], v[164:167], v[194:197], v[64:67]
	v_mfma_f32_16x16x32_bf16 v[64:67], v[180:183], v[188:191], v[112:115]
	v_mfma_f32_16x16x32_bf16 v[112:115], v[184:187], v[194:197], v[64:67]
	v_mfma_f32_16x16x32_bf16 v[64:67], v[160:163], v[198:201], v[100:103]
	v_mfma_f32_16x16x32_bf16 v[100:103], v[164:167], v[202:205], v[64:67]
	v_mfma_f32_16x16x32_bf16 v[64:67], v[180:183], v[198:201], v[96:99]
	v_mfma_f32_16x16x32_bf16 v[148:151], v[164:167], v[68:71], v[148:151]
	v_mfma_f32_16x16x32_bf16 v[96:99], v[184:187], v[202:205], v[64:67]
	s_barrier
	s_add_u32 s86, s84, 0x8000
	s_addc_u32 s87, s85, 0
	s_add_i32 m0, s57, 0x18000
	ds_read_b128 v[64:67], v193 offset:49152
	ds_read_b128 v[68:71], v193 offset:50176
	ds_read_b128 v[188:191], v193 offset:51200
	ds_read_b128 v[194:197], v193 offset:52224
	ds_read_b128 v[198:201], v193 offset:53248
	ds_read_b128 v[202:205], v193 offset:54272
	ds_read_b128 v[206:209], v193 offset:55296
	ds_read_b128 v[210:213], v193 offset:56320
	global_load_lds_dwordx4 v170, s[86:87]
	s_add_i32 m0, s57, 0x1a000
	s_add_u32 s84, s84, 0xc000
	s_addc_u32 s85, s85, 0
	global_load_lds_dwordx4 v174, s[86:87]
	s_add_i32 m0, s57, 0x1c000
	s_nop 0
	global_load_lds_dwordx4 v170, s[84:85]
	s_add_i32 m0, s57, 0x1e000
	s_nop 0
	global_load_lds_dwordx4 v174, s[84:85]
	s_mov_b32 m0, s53
	s_nop 0
	global_load_lds_dwordx4 v168, s[10:11]
	s_mov_b32 m0, s27
	s_nop 0
	global_load_lds_dwordx4 v172, s[10:11]
	s_waitcnt vmcnt(8) lgkmcnt(0)
	s_barrier
	v_mfma_f32_16x16x32_bf16 v[80:83], v[48:51], v[64:67], v[92:95]
	v_mfma_f32_16x16x32_bf16 v[92:95], v[52:55], v[68:71], v[80:83]
	v_mfma_f32_16x16x32_bf16 v[80:83], v[56:59], v[64:67], v[88:91]
	v_mfma_f32_16x16x32_bf16 v[76:79], v[48:51], v[188:191], v[76:79]
	v_mfma_f32_16x16x32_bf16 v[72:75], v[56:59], v[188:191], v[72:75]
	v_mfma_f32_16x16x32_bf16 v[44:47], v[48:51], v[198:201], v[44:47]
	v_mfma_f32_16x16x32_bf16 v[40:43], v[56:59], v[198:201], v[40:43]
	v_mfma_f32_16x16x32_bf16 v[12:15], v[48:51], v[206:209], v[12:15]
	v_mfma_f32_16x16x32_bf16 v[8:11], v[56:59], v[206:209], v[8:11]
	v_mfma_f32_16x16x32_bf16 v[88:91], v[60:63], v[68:71], v[80:83]
	v_mfma_f32_16x16x32_bf16 v[76:79], v[52:55], v[194:197], v[76:79]
	v_mfma_f32_16x16x32_bf16 v[72:75], v[60:63], v[194:197], v[72:75]
	v_mfma_f32_16x16x32_bf16 v[44:47], v[52:55], v[202:205], v[44:47]
	v_mfma_f32_16x16x32_bf16 v[40:43], v[60:63], v[202:205], v[40:43]
	v_mfma_f32_16x16x32_bf16 v[12:15], v[52:55], v[210:213], v[12:15]
	v_mfma_f32_16x16x32_bf16 v[8:11], v[60:63], v[210:213], v[8:11]
	v_mfma_f32_16x16x32_bf16 v[16:19], v[160:163], v[64:67], v[16:19]
	v_mfma_f32_16x16x32_bf16 v[84:87], v[164:167], v[68:71], v[16:19]
	v_mfma_f32_16x16x32_bf16 v[16:19], v[180:183], v[64:67], v[20:23]
	v_mfma_f32_16x16x32_bf16 v[80:83], v[184:187], v[68:71], v[16:19]
	v_mfma_f32_16x16x32_bf16 v[16:19], v[160:163], v[188:191], v[24:27]
	v_mfma_f32_16x16x32_bf16 v[68:71], v[164:167], v[194:197], v[16:19]
	v_mfma_f32_16x16x32_bf16 v[16:19], v[180:183], v[188:191], v[32:35]
	v_mfma_f32_16x16x32_bf16 v[64:67], v[184:187], v[194:197], v[16:19]
	v_mfma_f32_16x16x32_bf16 v[16:19], v[160:163], v[198:201], v[36:39]
	v_mfma_f32_16x16x32_bf16 v[36:39], v[164:167], v[202:205], v[16:19]
	v_mfma_f32_16x16x32_bf16 v[16:19], v[180:183], v[198:201], v[28:31]
	v_mfma_f32_16x16x32_bf16 v[4:7], v[160:163], v[206:209], v[4:7]
	v_mfma_f32_16x16x32_bf16 v[0:3], v[180:183], v[206:209], v[0:3]
	v_mfma_f32_16x16x32_bf16 v[28:31], v[184:187], v[202:205], v[16:19]
	v_mfma_f32_16x16x32_bf16 v[4:7], v[164:167], v[210:213], v[4:7]
	v_mfma_f32_16x16x32_bf16 v[0:3], v[184:187], v[210:213], v[0:3]
	s_barrier
	s_add_i32 s40, s40, 2
	s_add_u32 s6, s6, 0x10000
	s_addc_u32 s7, s7, 0
	s_add_u32 s30, s30, 0x10000
	s_addc_u32 s37, s37, 0
	s_cmp_gt_u32 s40, 13
	s_cbranch_scc0 .LBB0_1130
	s_and_b64 vcc, exec, s[70:71]
	s_cbranch_vccz .LBB0_1133
	s_barrier

; #define PG8_STAGE(bufoff, gbase, voff) do { _Pragma("unroll") for (int _i = 0; _i < 2; ++_i) \
;         __builtin_amdgcn_global_load_lds((const unsigned*)((const char*)(gbase) + (voff)[_i]), (PG8_LAS unsigned*)(lds + (bufoff) + ldsw + _i * 8192), 16, 0, 0); } while (0)
; #define PG8_LDA(dst, b, h) do { _Pragma("unroll") for (int m = 0; m < 4; ++m) _Pragma("unroll") for (int k = 0; k < 2; ++k) dst[m][k] = *(const PG8_LAS bf16x8*)(lds + PG8_SA(b, h) + aoff + m * 2048 + k * 1024); } while (0)
; #define PG8_LDB(dst, b, h) do { _Pragma("unroll") for (int n = 0; n < 2; ++n) _Pragma("unroll") for (int k = 0; k < 2; ++k) dst[n][k] = *(const PG8_LAS bf16x8*)(lds + PG8_SB(b, h) + boff + n * 2048 + k * 1024); } while (0)
; #define PG8_MMA(ai, bj, At, Bt) do { __builtin_amdgcn_s_setprio(1); _Pragma("unroll") for (int m = 0; m < 4; ++m) _Pragma("unroll") for (int n = 0; n < 2; ++n) _Pragma("unroll") for (int k = 0; k < 2; ++k) \
;         acc[ai][bj][m][n] = __builtin_amdgcn_mfma_f32_16x16x32_bf16(Bt[n][k], At[m][k], acc[ai][bj][m][n], 0, 0, 0); __builtin_amdgcn_s_setprio(0); } while (0)
; #define PG8_WAIT_V(n) asm volatile("s_waitcnt vmcnt(" #n ")" ::: "memory")
; #define PG8_WAIT_L(n) asm volatile("s_waitcnt lgkmcnt(" #n ")" ::: "memory")
; #define PG8_BAR __builtin_amdgcn_s_barrier()
; #define PG8_SCHED __builtin_amdgcn_sched_barrier(0)
; template <class Epi, class Sched, bool ALIGN_EPI = false, bool SP2 = false>
; __device__ __forceinline__ void gemm_phase(PG8_LAS unsigned char* lds, const Gemm g, const Sched& S, const Epi& E) {
;     ...
;         for (int t = 0; t < nt; t += 2) {
;             const bool last = (t == nt - 2);
;             const char* a1 = cA + (size_t)(t + 1) * kstep;
;             const char* a2 = last ? nA : cA + (size_t)(t + 2) * kstep; const char* b2 = last ? nB : cB + (size_t)(t + 2) * kstep;
;             const char* a3 = a2 + kstep; const char* b3 = b2 + kstep;
;             if (last && has_next) S.a_ready(nxt);
;             if constexpr (SP2) {
;             PG8_LDB(B0, 0, 0); PG8_LDB(B1, 0, 1); PG8_SCHED; PG8_LDA(At, 0, 0); PG8_STAGE(PG8_SA(1, 1), a1 + hstep, voffA);
;             PG8_WAIT_V(8); PG8_WAIT_L(0); PG8_BAR; PG8_MMA(0, 0, At, B0); PG8_MMA(0, 1, At, B1); PG8_BAR; PG8_SCHED;
;             PG8_LDA(At, 0, 1); PG8_STAGE(PG8_SB(0, 0), b2, voffB); PG8_STAGE(PG8_SB(0, 1), b2 + hstep, voffB); PG8_STAGE(PG8_SA(0, 0), a2, voffA);
.LBB0_1321:
	s_add_u32 s16, s16, 0xc000
	s_addc_u32 s17, s17, 0
	s_add_u32 s66, s18, 0x10000
	v_mov_b32_e32 v0, 0
	s_addc_u32 s67, s19, 0
	s_mov_b32 s18, 0
	v_add_u32_e32 v246, 0x10000, v206
	s_add_i32 s75, s18, 2
	s_add_u32 s19, s16, 0x4000
	s_addc_u32 s20, s17, 0
	s_cmp_eq_u32 s59, s18
	s_cselect_b32 s64, s0, s19
	s_cselect_b32 s65, s1, s20
	s_cselect_b32 s20, s14, s66
	s_cselect_b32 s21, s15, s67
	s_add_u32 s18, s64, 0x8000
	s_addc_u32 s19, s65, 0
	ds_read_b128 v[80:83], v246
	ds_read_b128 v[84:87], v246 offset:1024
	ds_read_b128 v[104:107], v246 offset:2048
	ds_read_b128 v[108:111], v246 offset:3072
	ds_read_b128 v[128:131], v246 offset:16384
	ds_read_b128 v[136:139], v246 offset:17408
	ds_read_b128 v[152:155], v246 offset:18432
	ds_read_b128 v[156:159], v246 offset:19456
	s_add_i32 m0, s41, 0xc000
	ds_read_b128 v[160:163], v207
	ds_read_b128 v[164:167], v207 offset:1024
	ds_read_b128 v[168:171], v207 offset:2048
	ds_read_b128 v[172:175], v207 offset:3072
	ds_read_b128 v[176:179], v207 offset:4096
	ds_read_b128 v[180:183], v207 offset:5120
	ds_read_b128 v[198:201], v207 offset:6144
	ds_read_b128 v[202:205], v207 offset:7168
	global_load_lds_dwordx4 v194, s[16:17]
	s_add_i32 m0, s41, 0xe000
	s_nop 0
	global_load_lds_dwordx4 v196, s[16:17]
	s_waitcnt vmcnt(8) lgkmcnt(0)
	s_barrier
	v_mfma_f32_16x16x32_bf16 v[148:151], v[80:83], v[160:163], 0
	v_mfma_f32_16x16x32_bf16 v[144:147], v[104:107], v[160:163], 0
	v_mfma_f32_16x16x32_bf16 v[124:127], v[80:83], v[168:171], 0
	v_mfma_f32_16x16x32_bf16 v[120:123], v[104:107], v[168:171], 0
	v_mfma_f32_16x16x32_bf16 v[100:103], v[80:83], v[176:179], 0
	v_mfma_f32_16x16x32_bf16 v[96:99], v[104:107], v[176:179], 0
	v_mfma_f32_16x16x32_bf16 v[76:79], v[80:83], v[198:201], 0
	v_mfma_f32_16x16x32_bf16 v[72:75], v[104:107], v[198:201], 0
	v_mfma_f32_16x16x32_bf16 v[148:151], v[84:87], v[164:167], v[148:151]
	v_mfma_f32_16x16x32_bf16 v[144:147], v[108:111], v[164:167], v[144:147]
	v_mfma_f32_16x16x32_bf16 v[124:127], v[84:87], v[172:175], v[124:127]
	v_mfma_f32_16x16x32_bf16 v[120:123], v[108:111], v[172:175], v[120:123]
	v_mfma_f32_16x16x32_bf16 v[100:103], v[84:87], v[180:183], v[100:103]
	v_mfma_f32_16x16x32_bf16 v[96:99], v[108:111], v[180:183], v[96:99]
	v_mfma_f32_16x16x32_bf16 v[76:79], v[84:87], v[202:205], v[76:79]
	v_mfma_f32_16x16x32_bf16 v[72:75], v[108:111], v[202:205], v[72:75]
	v_mfma_f32_16x16x32_bf16 v[140:143], v[128:131], v[160:163], 0
	v_mfma_f32_16x16x32_bf16 v[132:135], v[152:155], v[160:163], 0
	v_mfma_f32_16x16x32_bf16 v[116:119], v[128:131], v[168:171], 0
	v_mfma_f32_16x16x32_bf16 v[112:115], v[152:155], v[168:171], 0
	v_mfma_f32_16x16x32_bf16 v[92:95], v[128:131], v[176:179], 0
	v_mfma_f32_16x16x32_bf16 v[88:91], v[152:155], v[176:179], 0
	v_mfma_f32_16x16x32_bf16 v[68:71], v[128:131], v[198:201], 0
	v_mfma_f32_16x16x32_bf16 v[64:67], v[152:155], v[198:201], 0
	v_mfma_f32_16x16x32_bf16 v[140:143], v[136:139], v[164:167], v[140:143]
	v_mfma_f32_16x16x32_bf16 v[132:135], v[156:159], v[164:167], v[132:135]
	v_mfma_f32_16x16x32_bf16 v[116:119], v[136:139], v[172:175], v[116:119]
	v_mfma_f32_16x16x32_bf16 v[112:115], v[156:159], v[172:175], v[112:115]
	v_mfma_f32_16x16x32_bf16 v[92:95], v[136:139], v[180:183], v[92:95]
	v_mfma_f32_16x16x32_bf16 v[88:91], v[156:159], v[180:183], v[88:91]
	v_mfma_f32_16x16x32_bf16 v[68:71], v[136:139], v[202:205], v[68:71]
	v_mfma_f32_16x16x32_bf16 v[64:67], v[156:159], v[202:205], v[64:67]
	s_barrier
	s_add_i32 m0, s39, 0x10000
	ds_read_b128 v[160:163], v207 offset:16384
	ds_read_b128 v[164:167], v207 offset:17408
	ds_read_b128 v[168:171], v207 offset:18432
	ds_read_b128 v[172:175], v207 offset:19456
	ds_read_b128 v[176:179], v207 offset:20480
	ds_read_b128 v[180:183], v207 offset:21504
	ds_read_b128 v[198:201], v207 offset:22528
	ds_read_b128 v[202:205], v207 offset:23552
	global_load_lds_dwordx4 v186, s[20:21]
	s_add_i32 m0, s39, 0x12000
	s_add_u32 s76, s20, 0x4000
	s_addc_u32 s77, s21, 0
	global_load_lds_dwordx4 v190, s[20:21]
	s_add_i32 m0, s39, 0x14000
	s_nop 0
	global_load_lds_dwordx4 v186, s[76:77]
	s_add_i32 m0, s39, 0x16000
	s_nop 0
	global_load_lds_dwordx4 v190, s[76:77]
	s_mov_b32 m0, s41
	s_nop 0
	global_load_lds_dwordx4 v184, s[64:65]
	s_mov_b32 m0, s42
	s_nop 0
	global_load_lds_dwordx4 v188, s[64:65]
	s_waitcnt vmcnt(8) lgkmcnt(0)
	s_barrier
	v_mfma_f32_16x16x32_bf16 v[60:63], v[80:83], v[160:163], 0
	v_mfma_f32_16x16x32_bf16 v[56:59], v[104:107], v[160:163], 0
	v_mfma_f32_16x16x32_bf16 v[44:47], v[80:83], v[168:171], 0
	v_mfma_f32_16x16x32_bf16 v[40:43], v[104:107], v[168:171], 0
	v_mfma_f32_16x16x32_bf16 v[28:31], v[80:83], v[176:179], 0
	v_mfma_f32_16x16x32_bf16 v[24:27], v[104:107], v[176:179], 0
	v_mfma_f32_16x16x32_bf16 v[12:15], v[80:83], v[198:201], 0
	v_mfma_f32_16x16x32_bf16 v[8:11], v[104:107], v[198:201], 0
	v_mfma_f32_16x16x32_bf16 v[60:63], v[84:87], v[164:167], v[60:63]
	v_mfma_f32_16x16x32_bf16 v[56:59], v[108:111], v[164:167], v[56:59]
	v_mfma_f32_16x16x32_bf16 v[44:47], v[84:87], v[172:175], v[44:47]
	v_mfma_f32_16x16x32_bf16 v[40:43], v[108:111], v[172:175], v[40:43]
	v_mfma_f32_16x16x32_bf16 v[28:31], v[84:87], v[180:183], v[28:31]
	v_mfma_f32_16x16x32_bf16 v[24:27], v[108:111], v[180:183], v[24:27]
	v_mfma_f32_16x16x32_bf16 v[12:15], v[84:87], v[202:205], v[12:15]
	v_mfma_f32_16x16x32_bf16 v[8:11], v[108:111], v[202:205], v[8:11]
	v_mfma_f32_16x16x32_bf16 v[52:55], v[128:131], v[160:163], 0
	v_mfma_f32_16x16x32_bf16 v[48:51], v[152:155], v[160:163], 0
	v_mfma_f32_16x16x32_bf16 v[36:39], v[128:131], v[168:171], 0
	v_mfma_f32_16x16x32_bf16 v[32:35], v[152:155], v[168:171], 0
	v_mfma_f32_16x16x32_bf16 v[20:23], v[128:131], v[176:179], 0
	v_mfma_f32_16x16x32_bf16 v[16:19], v[152:155], v[176:179], 0
	v_mfma_f32_16x16x32_bf16 v[4:7], v[128:131], v[198:201], 0
	v_mfma_f32_16x16x32_bf16 v[0:3], v[152:155], v[198:201], 0
	v_mfma_f32_16x16x32_bf16 v[52:55], v[136:139], v[164:167], v[52:55]
	v_mfma_f32_16x16x32_bf16 v[48:51], v[156:159], v[164:167], v[48:51]
	v_mfma_f32_16x16x32_bf16 v[36:39], v[136:139], v[172:175], v[36:39]
	v_mfma_f32_16x16x32_bf16 v[32:35], v[156:159], v[172:175], v[32:35]
	v_mfma_f32_16x16x32_bf16 v[20:23], v[136:139], v[180:183], v[20:23]
	v_mfma_f32_16x16x32_bf16 v[16:19], v[156:159], v[180:183], v[16:19]
	v_mfma_f32_16x16x32_bf16 v[4:7], v[136:139], v[202:205], v[4:7]
	v_mfma_f32_16x16x32_bf16 v[0:3], v[156:159], v[202:205], v[0:3]
	s_barrier
; #define PG8_STAGE(bufoff, gbase, voff) do { _Pragma("unroll") for (int _i = 0; _i < 2; ++_i) \
;         __builtin_amdgcn_global_load_lds((const unsigned*)((const char*)(gbase) + (voff)[_i]), (PG8_LAS unsigned*)(lds + (bufoff) + ldsw + _i * 8192), 16, 0, 0); } while (0)
; #define PG8_LDA(dst, b, h) do { _Pragma("unroll") for (int m = 0; m < 4; ++m) _Pragma("unroll") for (int k = 0; k < 2; ++k) dst[m][k] = *(const PG8_LAS bf16x8*)(lds + PG8_SA(b, h) + aoff + m * 2048 + k * 1024); } while (0)
; #define PG8_LDB(dst, b, h) do { _Pragma("unroll") for (int n = 0; n < 2; ++n) _Pragma("unroll") for (int k = 0; k < 2; ++k) dst[n][k] = *(const PG8_LAS bf16x8*)(lds + PG8_SB(b, h) + boff + n * 2048 + k * 1024); } while (0)
; #define PG8_MMA(ai, bj, At, Bt) do { __builtin_amdgcn_s_setprio(1); _Pragma("unroll") for (int m = 0; m < 4; ++m) _Pragma("unroll") for (int n = 0; n < 2; ++n) _Pragma("unroll") for (int k = 0; k < 2; ++k) \
;         acc[ai][bj][m][n] = __builtin_amdgcn_mfma_f32_16x16x32_bf16(Bt[n][k], At[m][k], acc[ai][bj][m][n], 0, 0, 0); __builtin_amdgcn_s_setprio(0); } while (0)
; #define PG8_WAIT_V(n) asm volatile("s_waitcnt vmcnt(" #n ")" ::: "memory")
; #define PG8_WAIT_L(n) asm volatile("s_waitcnt lgkmcnt(" #n ")" ::: "memory")
; #define PG8_BAR __builtin_amdgcn_s_barrier()
; #define PG8_SCHED __builtin_amdgcn_sched_barrier(0)
; template <class Epi, class Sched, bool ALIGN_EPI = false, bool SP2 = false>
; __device__ __forceinline__ void gemm_phase(PG8_LAS unsigned char* lds, const Gemm g, const Sched& S, const Epi& E) {
;     ...
;             PG8_WAIT_V(8); PG8_WAIT_L(0); PG8_BAR; PG8_MMA(1, 0, At, B0); PG8_MMA(1, 1, At, B1); PG8_BAR; PG8_SCHED;
;             PG8_LDB(B0, 1, 0); PG8_LDB(B1, 1, 1); PG8_SCHED; PG8_LDA(At, 1, 0); PG8_STAGE(PG8_SA(0, 1), a2 + hstep, voffA);
;             PG8_WAIT_V(8); PG8_WAIT_L(0); PG8_BAR; PG8_MMA(0, 0, At, B0); PG8_MMA(0, 1, At, B1); PG8_BAR; PG8_SCHED;
;             PG8_LDA(At, 1, 1); PG8_STAGE(PG8_SB(1, 0), b3, voffB); PG8_STAGE(PG8_SB(1, 1), b3 + hstep, voffB); PG8_STAGE(PG8_SA(1, 0), a3, voffA);
;             PG8_WAIT_V(8); PG8_WAIT_L(0); PG8_BAR; PG8_MMA(1, 0, At, B0); PG8_MMA(1, 1, At, B1); PG8_BAR; PG8_SCHED;
	ds_read_b128 v[80:83], v246 offset:32768
	ds_read_b128 v[84:87], v246 offset:33792
	ds_read_b128 v[104:107], v246 offset:34816
	ds_read_b128 v[108:111], v246 offset:35840
	ds_read_b128 v[128:131], v246 offset:49152
	ds_read_b128 v[136:139], v246 offset:50176
	ds_read_b128 v[152:155], v246 offset:51200
	ds_read_b128 v[156:159], v246 offset:52224
	s_add_u32 s64, s64, 0x4000
	s_addc_u32 s65, s65, 0
	s_mov_b32 m0, s50
	ds_read_b128 v[160:163], v207 offset:32768
	ds_read_b128 v[164:167], v207 offset:33792
	ds_read_b128 v[168:171], v207 offset:34816
	ds_read_b128 v[172:175], v207 offset:35840
	ds_read_b128 v[176:179], v207 offset:36864
	ds_read_b128 v[180:183], v207 offset:37888
	ds_read_b128 v[198:201], v207 offset:38912
	ds_read_b128 v[202:205], v207 offset:39936
	global_load_lds_dwordx4 v184, s[64:65]
	s_mov_b32 m0, s51
	s_nop 0
	global_load_lds_dwordx4 v188, s[64:65]
	s_waitcnt vmcnt(8) lgkmcnt(0)
	s_barrier
	v_mfma_f32_16x16x32_bf16 v[148:151], v[80:83], v[160:163], v[148:151]
	v_mfma_f32_16x16x32_bf16 v[144:147], v[104:107], v[160:163], v[144:147]
	v_mfma_f32_16x16x32_bf16 v[124:127], v[80:83], v[168:171], v[124:127]
	v_mfma_f32_16x16x32_bf16 v[120:123], v[104:107], v[168:171], v[120:123]
	v_mfma_f32_16x16x32_bf16 v[100:103], v[80:83], v[176:179], v[100:103]
	v_mfma_f32_16x16x32_bf16 v[96:99], v[104:107], v[176:179], v[96:99]
	v_mfma_f32_16x16x32_bf16 v[76:79], v[80:83], v[198:201], v[76:79]
	v_mfma_f32_16x16x32_bf16 v[72:75], v[104:107], v[198:201], v[72:75]
	v_mfma_f32_16x16x32_bf16 v[148:151], v[84:87], v[164:167], v[148:151]
	v_mfma_f32_16x16x32_bf16 v[144:147], v[108:111], v[164:167], v[144:147]
	v_mfma_f32_16x16x32_bf16 v[124:127], v[84:87], v[172:175], v[124:127]
	v_mfma_f32_16x16x32_bf16 v[120:123], v[108:111], v[172:175], v[120:123]
	v_mfma_f32_16x16x32_bf16 v[100:103], v[84:87], v[180:183], v[100:103]
	v_mfma_f32_16x16x32_bf16 v[96:99], v[108:111], v[180:183], v[96:99]
	v_mfma_f32_16x16x32_bf16 v[76:79], v[84:87], v[202:205], v[76:79]
	v_mfma_f32_16x16x32_bf16 v[72:75], v[108:111], v[202:205], v[72:75]
	v_mfma_f32_16x16x32_bf16 v[140:143], v[128:131], v[160:163], v[140:143]
	v_mfma_f32_16x16x32_bf16 v[132:135], v[152:155], v[160:163], v[132:135]
	v_mfma_f32_16x16x32_bf16 v[116:119], v[128:131], v[168:171], v[116:119]
	v_mfma_f32_16x16x32_bf16 v[112:115], v[152:155], v[168:171], v[112:115]
	v_mfma_f32_16x16x32_bf16 v[92:95], v[128:131], v[176:179], v[92:95]
	v_mfma_f32_16x16x32_bf16 v[88:91], v[152:155], v[176:179], v[88:91]
	v_mfma_f32_16x16x32_bf16 v[68:71], v[128:131], v[198:201], v[68:71]
	v_mfma_f32_16x16x32_bf16 v[64:67], v[152:155], v[198:201], v[64:67]
	v_mfma_f32_16x16x32_bf16 v[140:143], v[136:139], v[164:167], v[140:143]
	v_mfma_f32_16x16x32_bf16 v[132:135], v[156:159], v[164:167], v[132:135]
	v_mfma_f32_16x16x32_bf16 v[116:119], v[136:139], v[172:175], v[116:119]
	v_mfma_f32_16x16x32_bf16 v[112:115], v[156:159], v[172:175], v[112:115]
	v_mfma_f32_16x16x32_bf16 v[92:95], v[136:139], v[180:183], v[92:95]
	v_mfma_f32_16x16x32_bf16 v[88:91], v[156:159], v[180:183], v[88:91]
	v_mfma_f32_16x16x32_bf16 v[68:71], v[136:139], v[202:205], v[68:71]
	v_mfma_f32_16x16x32_bf16 v[64:67], v[156:159], v[202:205], v[64:67]
	s_barrier
	s_add_u32 s64, s20, 0x8000
	s_addc_u32 s65, s21, 0
	s_add_i32 m0, s39, 0x18000
	ds_read_b128 v[160:163], v207 offset:49152
	ds_read_b128 v[164:167], v207 offset:50176
	ds_read_b128 v[168:171], v207 offset:51200
	ds_read_b128 v[172:175], v207 offset:52224
	ds_read_b128 v[176:179], v207 offset:53248
	ds_read_b128 v[180:183], v207 offset:54272
	ds_read_b128 v[198:201], v207 offset:55296
	ds_read_b128 v[202:205], v207 offset:56320
	global_load_lds_dwordx4 v186, s[64:65]
	s_add_i32 m0, s39, 0x1a000
	s_add_u32 s20, s20, 0xc000
	s_addc_u32 s21, s21, 0
	global_load_lds_dwordx4 v190, s[64:65]
	s_add_i32 m0, s39, 0x1c000
	s_nop 0
	global_load_lds_dwordx4 v186, s[20:21]
	s_add_i32 m0, s39, 0x1e000
	s_nop 0
	global_load_lds_dwordx4 v190, s[20:21]
	s_mov_b32 m0, s56
	s_nop 0
	global_load_lds_dwordx4 v184, s[18:19]
	s_mov_b32 m0, s57
	s_nop 0
	global_load_lds_dwordx4 v188, s[18:19]
	s_waitcnt vmcnt(8) lgkmcnt(0)
	s_barrier
	v_mfma_f32_16x16x32_bf16 v[60:63], v[80:83], v[160:163], v[60:63]
	v_mfma_f32_16x16x32_bf16 v[56:59], v[104:107], v[160:163], v[56:59]
	v_mfma_f32_16x16x32_bf16 v[44:47], v[80:83], v[168:171], v[44:47]
	v_mfma_f32_16x16x32_bf16 v[40:43], v[104:107], v[168:171], v[40:43]
	v_mfma_f32_16x16x32_bf16 v[28:31], v[80:83], v[176:179], v[28:31]
	v_mfma_f32_16x16x32_bf16 v[24:27], v[104:107], v[176:179], v[24:27]
	v_mfma_f32_16x16x32_bf16 v[12:15], v[80:83], v[198:201], v[12:15]
	v_mfma_f32_16x16x32_bf16 v[8:11], v[104:107], v[198:201], v[8:11]
	v_mfma_f32_16x16x32_bf16 v[60:63], v[84:87], v[164:167], v[60:63]
	v_mfma_f32_16x16x32_bf16 v[56:59], v[108:111], v[164:167], v[56:59]
	v_mfma_f32_16x16x32_bf16 v[44:47], v[84:87], v[172:175], v[44:47]
	v_mfma_f32_16x16x32_bf16 v[40:43], v[108:111], v[172:175], v[40:43]
	v_mfma_f32_16x16x32_bf16 v[28:31], v[84:87], v[180:183], v[28:31]
	v_mfma_f32_16x16x32_bf16 v[24:27], v[108:111], v[180:183], v[24:27]
	v_mfma_f32_16x16x32_bf16 v[12:15], v[84:87], v[202:205], v[12:15]
	v_mfma_f32_16x16x32_bf16 v[8:11], v[108:111], v[202:205], v[8:11]
	v_mfma_f32_16x16x32_bf16 v[52:55], v[128:131], v[160:163], v[52:55]
	v_mfma_f32_16x16x32_bf16 v[48:51], v[152:155], v[160:163], v[48:51]
	v_mfma_f32_16x16x32_bf16 v[36:39], v[128:131], v[168:171], v[36:39]
	v_mfma_f32_16x16x32_bf16 v[32:35], v[152:155], v[168:171], v[32:35]
	v_mfma_f32_16x16x32_bf16 v[20:23], v[128:131], v[176:179], v[20:23]
	v_mfma_f32_16x16x32_bf16 v[16:19], v[152:155], v[176:179], v[16:19]
	v_mfma_f32_16x16x32_bf16 v[4:7], v[128:131], v[198:201], v[4:7]
	v_mfma_f32_16x16x32_bf16 v[0:3], v[152:155], v[198:201], v[0:3]
	v_mfma_f32_16x16x32_bf16 v[52:55], v[136:139], v[164:167], v[52:55]
	v_mfma_f32_16x16x32_bf16 v[48:51], v[156:159], v[164:167], v[48:51]
	v_mfma_f32_16x16x32_bf16 v[36:39], v[136:139], v[172:175], v[36:39]
	v_mfma_f32_16x16x32_bf16 v[32:35], v[156:159], v[172:175], v[32:35]
	v_mfma_f32_16x16x32_bf16 v[20:23], v[136:139], v[180:183], v[20:23]
	v_mfma_f32_16x16x32_bf16 v[16:19], v[156:159], v[180:183], v[16:19]
	v_mfma_f32_16x16x32_bf16 v[4:7], v[136:139], v[202:205], v[4:7]
	v_mfma_f32_16x16x32_bf16 v[0:3], v[156:159], v[202:205], v[0:3]
	s_barrier
	s_add_u32 s16, s16, 0x10000
	s_addc_u32 s17, s17, 0
	s_add_u32 s66, s66, 0x10000
	s_addc_u32 s67, s67, 0
	s_cmp_ge_u32 s75, s53
	s_mov_b32 s18, s75
; #define PG8_STAGE(bufoff, gbase, voff) do { _Pragma("unroll") for (int _i = 0; _i < 2; ++_i) \
;         __builtin_amdgcn_global_load_lds((const unsigned*)((const char*)(gbase) + (voff)[_i]), (PG8_LAS unsigned*)(lds + (bufoff) + ldsw + _i * 8192), 16, 0, 0); } while (0)
; #define PG8_LDA(dst, b, h) do { _Pragma("unroll") for (int m = 0; m < 4; ++m) _Pragma("unroll") for (int k = 0; k < 2; ++k) dst[m][k] = *(const PG8_LAS bf16x8*)(lds + PG8_SA(b, h) + aoff + m * 2048 + k * 1024); } while (0)
; #define PG8_LDB(dst, b, h) do { _Pragma("unroll") for (int n = 0; n < 2; ++n) _Pragma("unroll") for (int k = 0; k < 2; ++k) dst[n][k] = *(const PG8_LAS bf16x8*)(lds + PG8_SB(b, h) + boff + n * 2048 + k * 1024); } while (0)
; #define PG8_MMA(ai, bj, At, Bt) do { __builtin_amdgcn_s_setprio(1); _Pragma("unroll") for (int m = 0; m < 4; ++m) _Pragma("unroll") for (int n = 0; n < 2; ++n) _Pragma("unroll") for (int k = 0; k < 2; ++k) \
;         acc[ai][bj][m][n] = __builtin_amdgcn_mfma_f32_16x16x32_bf16(Bt[n][k], At[m][k], acc[ai][bj][m][n], 0, 0, 0); __builtin_amdgcn_s_setprio(0); } while (0)
; #define PG8_WAIT_V(n) asm volatile("s_waitcnt vmcnt(" #n ")" ::: "memory")
; #define PG8_WAIT_L(n) asm volatile("s_waitcnt lgkmcnt(" #n ")" ::: "memory")
; #define PG8_BAR __builtin_amdgcn_s_barrier()
; #define PG8_SCHED __builtin_amdgcn_sched_barrier(0)
; template <class Epi, class Sched, bool ALIGN_EPI = false, bool SP2 = false>
; __device__ __forceinline__ void gemm_phase(PG8_LAS unsigned char* lds, const Gemm g, const Sched& S, const Epi& E) {
;     ...
;         for (int t = 0; t < nt; t += 2) {
;             const bool last = (t == nt - 2);
;             const char* a1 = cA + (size_t)(t + 1) * kstep;
;             const char* a2 = last ? nA : cA + (size_t)(t + 2) * kstep; const char* b2 = last ? nB : cB + (size_t)(t + 2) * kstep;
;             const char* a3 = a2 + kstep; const char* b3 = b2 + kstep;
;             if (last && has_next) S.a_ready(nxt);
;             if constexpr (SP2) {
;             PG8_LDB(B0, 0, 0); PG8_LDB(B1, 0, 1); PG8_SCHED; PG8_LDA(At, 0, 0); PG8_STAGE(PG8_SA(1, 1), a1 + hstep, voffA);
;             PG8_WAIT_V(8); PG8_WAIT_L(0); PG8_BAR; PG8_MMA(0, 0, At, B0); PG8_MMA(0, 1, At, B1); PG8_BAR; PG8_SCHED;
;             PG8_LDA(At, 0, 1); PG8_STAGE(PG8_SB(0, 0), b2, voffB); PG8_STAGE(PG8_SB(0, 1), b2 + hstep, voffB); PG8_STAGE(PG8_SA(0, 0), a2, voffA);
.LBB0_1322:
	s_add_i32 s75, s18, 2
	s_add_u32 s19, s16, 0x4000
	s_addc_u32 s20, s17, 0
	s_cmp_eq_u32 s59, s18
	s_cselect_b32 s64, s0, s19
	s_cselect_b32 s65, s1, s20
	s_cselect_b32 s20, s14, s66
	s_cselect_b32 s21, s15, s67
	s_add_u32 s18, s64, 0x8000
	s_addc_u32 s19, s65, 0
	ds_read_b128 v[80:83], v246
	ds_read_b128 v[84:87], v246 offset:1024
	ds_read_b128 v[104:107], v246 offset:2048
	ds_read_b128 v[108:111], v246 offset:3072
	ds_read_b128 v[128:131], v246 offset:16384
	ds_read_b128 v[136:139], v246 offset:17408
	ds_read_b128 v[152:155], v246 offset:18432
	ds_read_b128 v[156:159], v246 offset:19456
	s_add_i32 m0, s41, 0xc000
	ds_read_b128 v[160:163], v207
	ds_read_b128 v[164:167], v207 offset:1024
	ds_read_b128 v[168:171], v207 offset:2048
	ds_read_b128 v[172:175], v207 offset:3072
	ds_read_b128 v[176:179], v207 offset:4096
	ds_read_b128 v[180:183], v207 offset:5120
	ds_read_b128 v[198:201], v207 offset:6144
	ds_read_b128 v[202:205], v207 offset:7168
	global_load_lds_dwordx4 v194, s[16:17]
	s_add_i32 m0, s41, 0xe000
	s_nop 0
	global_load_lds_dwordx4 v196, s[16:17]
	s_waitcnt vmcnt(8) lgkmcnt(0)
	s_barrier
	v_mfma_f32_16x16x32_bf16 v[148:151], v[80:83], v[160:163], v[148:151]
	v_mfma_f32_16x16x32_bf16 v[144:147], v[104:107], v[160:163], v[144:147]
	v_mfma_f32_16x16x32_bf16 v[124:127], v[80:83], v[168:171], v[124:127]
	v_mfma_f32_16x16x32_bf16 v[120:123], v[104:107], v[168:171], v[120:123]
	v_mfma_f32_16x16x32_bf16 v[100:103], v[80:83], v[176:179], v[100:103]
	v_mfma_f32_16x16x32_bf16 v[96:99], v[104:107], v[176:179], v[96:99]
	v_mfma_f32_16x16x32_bf16 v[76:79], v[80:83], v[198:201], v[76:79]
	v_mfma_f32_16x16x32_bf16 v[72:75], v[104:107], v[198:201], v[72:75]
	v_mfma_f32_16x16x32_bf16 v[148:151], v[84:87], v[164:167], v[148:151]
	v_mfma_f32_16x16x32_bf16 v[144:147], v[108:111], v[164:167], v[144:147]
	v_mfma_f32_16x16x32_bf16 v[124:127], v[84:87], v[172:175], v[124:127]
	v_mfma_f32_16x16x32_bf16 v[120:123], v[108:111], v[172:175], v[120:123]
	v_mfma_f32_16x16x32_bf16 v[100:103], v[84:87], v[180:183], v[100:103]
	v_mfma_f32_16x16x32_bf16 v[96:99], v[108:111], v[180:183], v[96:99]
	v_mfma_f32_16x16x32_bf16 v[76:79], v[84:87], v[202:205], v[76:79]
	v_mfma_f32_16x16x32_bf16 v[72:75], v[108:111], v[202:205], v[72:75]
	v_mfma_f32_16x16x32_bf16 v[140:143], v[128:131], v[160:163], v[140:143]
	v_mfma_f32_16x16x32_bf16 v[132:135], v[152:155], v[160:163], v[132:135]
	v_mfma_f32_16x16x32_bf16 v[116:119], v[128:131], v[168:171], v[116:119]
	v_mfma_f32_16x16x32_bf16 v[112:115], v[152:155], v[168:171], v[112:115]
	v_mfma_f32_16x16x32_bf16 v[92:95], v[128:131], v[176:179], v[92:95]
	v_mfma_f32_16x16x32_bf16 v[88:91], v[152:155], v[176:179], v[88:91]
	v_mfma_f32_16x16x32_bf16 v[68:71], v[128:131], v[198:201], v[68:71]
	v_mfma_f32_16x16x32_bf16 v[64:67], v[152:155], v[198:201], v[64:67]
	v_mfma_f32_16x16x32_bf16 v[140:143], v[136:139], v[164:167], v[140:143]
	v_mfma_f32_16x16x32_bf16 v[132:135], v[156:159], v[164:167], v[132:135]
	v_mfma_f32_16x16x32_bf16 v[116:119], v[136:139], v[172:175], v[116:119]
	v_mfma_f32_16x16x32_bf16 v[112:115], v[156:159], v[172:175], v[112:115]
	v_mfma_f32_16x16x32_bf16 v[92:95], v[136:139], v[180:183], v[92:95]
	v_mfma_f32_16x16x32_bf16 v[88:91], v[156:159], v[180:183], v[88:91]
	v_mfma_f32_16x16x32_bf16 v[68:71], v[136:139], v[202:205], v[68:71]
	v_mfma_f32_16x16x32_bf16 v[64:67], v[156:159], v[202:205], v[64:67]
	s_barrier
	s_add_i32 m0, s39, 0x10000
	ds_read_b128 v[160:163], v207 offset:16384
	ds_read_b128 v[164:167], v207 offset:17408
	ds_read_b128 v[168:171], v207 offset:18432
	ds_read_b128 v[172:175], v207 offset:19456
	ds_read_b128 v[176:179], v207 offset:20480
	ds_read_b128 v[180:183], v207 offset:21504
	ds_read_b128 v[198:201], v207 offset:22528
	ds_read_b128 v[202:205], v207 offset:23552
	global_load_lds_dwordx4 v186, s[20:21]
	s_add_i32 m0, s39, 0x12000
	s_add_u32 s76, s20, 0x4000
	s_addc_u32 s77, s21, 0
	global_load_lds_dwordx4 v190, s[20:21]
	s_add_i32 m0, s39, 0x14000
	s_nop 0
	global_load_lds_dwordx4 v186, s[76:77]
	s_add_i32 m0, s39, 0x16000
	s_nop 0
	global_load_lds_dwordx4 v190, s[76:77]
	s_mov_b32 m0, s41
	s_nop 0
	global_load_lds_dwordx4 v184, s[64:65]
	s_mov_b32 m0, s42
	s_nop 0
	global_load_lds_dwordx4 v188, s[64:65]
	s_waitcnt vmcnt(8) lgkmcnt(0)
	s_barrier
	v_mfma_f32_16x16x32_bf16 v[60:63], v[80:83], v[160:163], v[60:63]
	v_mfma_f32_16x16x32_bf16 v[56:59], v[104:107], v[160:163], v[56:59]
	v_mfma_f32_16x16x32_bf16 v[44:47], v[80:83], v[168:171], v[44:47]
	v_mfma_f32_16x16x32_bf16 v[40:43], v[104:107], v[168:171], v[40:43]
	v_mfma_f32_16x16x32_bf16 v[28:31], v[80:83], v[176:179], v[28:31]
	v_mfma_f32_16x16x32_bf16 v[24:27], v[104:107], v[176:179], v[24:27]
	v_mfma_f32_16x16x32_bf16 v[12:15], v[80:83], v[198:201], v[12:15]
	v_mfma_f32_16x16x32_bf16 v[8:11], v[104:107], v[198:201], v[8:11]
	v_mfma_f32_16x16x32_bf16 v[60:63], v[84:87], v[164:167], v[60:63]
	v_mfma_f32_16x16x32_bf16 v[56:59], v[108:111], v[164:167], v[56:59]
	v_mfma_f32_16x16x32_bf16 v[44:47], v[84:87], v[172:175], v[44:47]
	v_mfma_f32_16x16x32_bf16 v[40:43], v[108:111], v[172:175], v[40:43]
	v_mfma_f32_16x16x32_bf16 v[28:31], v[84:87], v[180:183], v[28:31]
	v_mfma_f32_16x16x32_bf16 v[24:27], v[108:111], v[180:183], v[24:27]
	v_mfma_f32_16x16x32_bf16 v[12:15], v[84:87], v[202:205], v[12:15]
	v_mfma_f32_16x16x32_bf16 v[8:11], v[108:111], v[202:205], v[8:11]
	v_mfma_f32_16x16x32_bf16 v[52:55], v[128:131], v[160:163], v[52:55]
	v_mfma_f32_16x16x32_bf16 v[48:51], v[152:155], v[160:163], v[48:51]
	v_mfma_f32_16x16x32_bf16 v[36:39], v[128:131], v[168:171], v[36:39]
	v_mfma_f32_16x16x32_bf16 v[32:35], v[152:155], v[168:171], v[32:35]
	v_mfma_f32_16x16x32_bf16 v[20:23], v[128:131], v[176:179], v[20:23]
	v_mfma_f32_16x16x32_bf16 v[16:19], v[152:155], v[176:179], v[16:19]
	v_mfma_f32_16x16x32_bf16 v[4:7], v[128:131], v[198:201], v[4:7]
	v_mfma_f32_16x16x32_bf16 v[0:3], v[152:155], v[198:201], v[0:3]
	v_mfma_f32_16x16x32_bf16 v[52:55], v[136:139], v[164:167], v[52:55]
	v_mfma_f32_16x16x32_bf16 v[48:51], v[156:159], v[164:167], v[48:51]
	v_mfma_f32_16x16x32_bf16 v[36:39], v[136:139], v[172:175], v[36:39]
	v_mfma_f32_16x16x32_bf16 v[32:35], v[156:159], v[172:175], v[32:35]
	v_mfma_f32_16x16x32_bf16 v[20:23], v[136:139], v[180:183], v[20:23]
	v_mfma_f32_16x16x32_bf16 v[16:19], v[156:159], v[180:183], v[16:19]
	v_mfma_f32_16x16x32_bf16 v[4:7], v[136:139], v[202:205], v[4:7]
	v_mfma_f32_16x16x32_bf16 v[0:3], v[156:159], v[202:205], v[0:3]
	s_barrier
; #define PG8_STAGE(bufoff, gbase, voff) do { _Pragma("unroll") for (int _i = 0; _i < 2; ++_i) \
;         __builtin_amdgcn_global_load_lds((const unsigned*)((const char*)(gbase) + (voff)[_i]), (PG8_LAS unsigned*)(lds + (bufoff) + ldsw + _i * 8192), 16, 0, 0); } while (0)
; #define PG8_LDA(dst, b, h) do { _Pragma("unroll") for (int m = 0; m < 4; ++m) _Pragma("unroll") for (int k = 0; k < 2; ++k) dst[m][k] = *(const PG8_LAS bf16x8*)(lds + PG8_SA(b, h) + aoff + m * 2048 + k * 1024); } while (0)
; #define PG8_LDB(dst, b, h) do { _Pragma("unroll") for (int n = 0; n < 2; ++n) _Pragma("unroll") for (int k = 0; k < 2; ++k) dst[n][k] = *(const PG8_LAS bf16x8*)(lds + PG8_SB(b, h) + boff + n * 2048 + k * 1024); } while (0)
; #define PG8_MMA(ai, bj, At, Bt) do { __builtin_amdgcn_s_setprio(1); _Pragma("unroll") for (int m = 0; m < 4; ++m) _Pragma("unroll") for (int n = 0; n < 2; ++n) _Pragma("unroll") for (int k = 0; k < 2; ++k) \
;         acc[ai][bj][m][n] = __builtin_amdgcn_mfma_f32_16x16x32_bf16(Bt[n][k], At[m][k], acc[ai][bj][m][n], 0, 0, 0); __builtin_amdgcn_s_setprio(0); } while (0)
; #define PG8_WAIT_V(n) asm volatile("s_waitcnt vmcnt(" #n ")" ::: "memory")
; #define PG8_WAIT_L(n) asm volatile("s_waitcnt lgkmcnt(" #n ")" ::: "memory")
; #define PG8_BAR __builtin_amdgcn_s_barrier()
; #define PG8_SCHED __builtin_amdgcn_sched_barrier(0)
; template <class Epi, class Sched, bool ALIGN_EPI = false, bool SP2 = false>
; __device__ __forceinline__ void gemm_phase(PG8_LAS unsigned char* lds, const Gemm g, const Sched& S, const Epi& E) {
;     ...
;             PG8_WAIT_V(8); PG8_WAIT_L(0); PG8_BAR; PG8_MMA(1, 0, At, B0); PG8_MMA(1, 1, At, B1); PG8_BAR; PG8_SCHED;
;             PG8_LDB(B0, 1, 0); PG8_LDB(B1, 1, 1); PG8_SCHED; PG8_LDA(At, 1, 0); PG8_STAGE(PG8_SA(0, 1), a2 + hstep, voffA);
;             PG8_WAIT_V(8); PG8_WAIT_L(0); PG8_BAR; PG8_MMA(0, 0, At, B0); PG8_MMA(0, 1, At, B1); PG8_BAR; PG8_SCHED;
;             PG8_LDA(At, 1, 1); PG8_STAGE(PG8_SB(1, 0), b3, voffB); PG8_STAGE(PG8_SB(1, 1), b3 + hstep, voffB); PG8_STAGE(PG8_SA(1, 0), a3, voffA);
;             PG8_WAIT_V(8); PG8_WAIT_L(0); PG8_BAR; PG8_MMA(1, 0, At, B0); PG8_MMA(1, 1, At, B1); PG8_BAR; PG8_SCHED;
	ds_read_b128 v[80:83], v246 offset:32768
	ds_read_b128 v[84:87], v246 offset:33792
	ds_read_b128 v[104:107], v246 offset:34816
	ds_read_b128 v[108:111], v246 offset:35840
	ds_read_b128 v[128:131], v246 offset:49152
	ds_read_b128 v[136:139], v246 offset:50176
	ds_read_b128 v[152:155], v246 offset:51200
	ds_read_b128 v[156:159], v246 offset:52224
	s_add_u32 s64, s64, 0x4000
	s_addc_u32 s65, s65, 0
	s_mov_b32 m0, s50
	ds_read_b128 v[160:163], v207 offset:32768
	ds_read_b128 v[164:167], v207 offset:33792
	ds_read_b128 v[168:171], v207 offset:34816
	ds_read_b128 v[172:175], v207 offset:35840
	ds_read_b128 v[176:179], v207 offset:36864
	ds_read_b128 v[180:183], v207 offset:37888
	ds_read_b128 v[198:201], v207 offset:38912
	ds_read_b128 v[202:205], v207 offset:39936
	global_load_lds_dwordx4 v184, s[64:65]
	s_mov_b32 m0, s51
	s_nop 0
	global_load_lds_dwordx4 v188, s[64:65]
	s_waitcnt vmcnt(8) lgkmcnt(0)
	s_barrier
	v_mfma_f32_16x16x32_bf16 v[148:151], v[80:83], v[160:163], v[148:151]
	v_mfma_f32_16x16x32_bf16 v[144:147], v[104:107], v[160:163], v[144:147]
	v_mfma_f32_16x16x32_bf16 v[124:127], v[80:83], v[168:171], v[124:127]
	v_mfma_f32_16x16x32_bf16 v[120:123], v[104:107], v[168:171], v[120:123]
	v_mfma_f32_16x16x32_bf16 v[100:103], v[80:83], v[176:179], v[100:103]
	v_mfma_f32_16x16x32_bf16 v[96:99], v[104:107], v[176:179], v[96:99]
	v_mfma_f32_16x16x32_bf16 v[76:79], v[80:83], v[198:201], v[76:79]
	v_mfma_f32_16x16x32_bf16 v[72:75], v[104:107], v[198:201], v[72:75]
	v_mfma_f32_16x16x32_bf16 v[148:151], v[84:87], v[164:167], v[148:151]
	v_mfma_f32_16x16x32_bf16 v[144:147], v[108:111], v[164:167], v[144:147]
	v_mfma_f32_16x16x32_bf16 v[124:127], v[84:87], v[172:175], v[124:127]
	v_mfma_f32_16x16x32_bf16 v[120:123], v[108:111], v[172:175], v[120:123]
	v_mfma_f32_16x16x32_bf16 v[100:103], v[84:87], v[180:183], v[100:103]
	v_mfma_f32_16x16x32_bf16 v[96:99], v[108:111], v[180:183], v[96:99]
	v_mfma_f32_16x16x32_bf16 v[76:79], v[84:87], v[202:205], v[76:79]
	v_mfma_f32_16x16x32_bf16 v[72:75], v[108:111], v[202:205], v[72:75]
	v_mfma_f32_16x16x32_bf16 v[140:143], v[128:131], v[160:163], v[140:143]
	v_mfma_f32_16x16x32_bf16 v[132:135], v[152:155], v[160:163], v[132:135]
	v_mfma_f32_16x16x32_bf16 v[116:119], v[128:131], v[168:171], v[116:119]
	v_mfma_f32_16x16x32_bf16 v[112:115], v[152:155], v[168:171], v[112:115]
	v_mfma_f32_16x16x32_bf16 v[92:95], v[128:131], v[176:179], v[92:95]
	v_mfma_f32_16x16x32_bf16 v[88:91], v[152:155], v[176:179], v[88:91]
	v_mfma_f32_16x16x32_bf16 v[68:71], v[128:131], v[198:201], v[68:71]
	v_mfma_f32_16x16x32_bf16 v[64:67], v[152:155], v[198:201], v[64:67]
	v_mfma_f32_16x16x32_bf16 v[140:143], v[136:139], v[164:167], v[140:143]
	v_mfma_f32_16x16x32_bf16 v[132:135], v[156:159], v[164:167], v[132:135]
	v_mfma_f32_16x16x32_bf16 v[116:119], v[136:139], v[172:175], v[116:119]
	v_mfma_f32_16x16x32_bf16 v[112:115], v[156:159], v[172:175], v[112:115]
	v_mfma_f32_16x16x32_bf16 v[92:95], v[136:139], v[180:183], v[92:95]
	v_mfma_f32_16x16x32_bf16 v[88:91], v[156:159], v[180:183], v[88:91]
	v_mfma_f32_16x16x32_bf16 v[68:71], v[136:139], v[202:205], v[68:71]
	v_mfma_f32_16x16x32_bf16 v[64:67], v[156:159], v[202:205], v[64:67]
	s_barrier
	s_add_u32 s64, s20, 0x8000
	s_addc_u32 s65, s21, 0
	s_add_i32 m0, s39, 0x18000
	ds_read_b128 v[160:163], v207 offset:49152
	ds_read_b128 v[164:167], v207 offset:50176
	ds_read_b128 v[168:171], v207 offset:51200
	ds_read_b128 v[172:175], v207 offset:52224
	ds_read_b128 v[176:179], v207 offset:53248
	ds_read_b128 v[180:183], v207 offset:54272
	ds_read_b128 v[198:201], v207 offset:55296
	ds_read_b128 v[202:205], v207 offset:56320
	global_load_lds_dwordx4 v186, s[64:65]
	s_add_i32 m0, s39, 0x1a000
	s_add_u32 s20, s20, 0xc000
	s_addc_u32 s21, s21, 0
	global_load_lds_dwordx4 v190, s[64:65]
	s_add_i32 m0, s39, 0x1c000
	s_nop 0
	global_load_lds_dwordx4 v186, s[20:21]
	s_add_i32 m0, s39, 0x1e000
	s_nop 0
	global_load_lds_dwordx4 v190, s[20:21]
	s_mov_b32 m0, s56
	s_nop 0
	global_load_lds_dwordx4 v184, s[18:19]
	s_mov_b32 m0, s57
	s_nop 0
	global_load_lds_dwordx4 v188, s[18:19]
	s_waitcnt vmcnt(8) lgkmcnt(0)
	s_barrier
	v_mfma_f32_16x16x32_bf16 v[60:63], v[80:83], v[160:163], v[60:63]
	v_mfma_f32_16x16x32_bf16 v[56:59], v[104:107], v[160:163], v[56:59]
	v_mfma_f32_16x16x32_bf16 v[44:47], v[80:83], v[168:171], v[44:47]
	v_mfma_f32_16x16x32_bf16 v[40:43], v[104:107], v[168:171], v[40:43]
	v_mfma_f32_16x16x32_bf16 v[28:31], v[80:83], v[176:179], v[28:31]
	v_mfma_f32_16x16x32_bf16 v[24:27], v[104:107], v[176:179], v[24:27]
	v_mfma_f32_16x16x32_bf16 v[12:15], v[80:83], v[198:201], v[12:15]
	v_mfma_f32_16x16x32_bf16 v[8:11], v[104:107], v[198:201], v[8:11]
	v_mfma_f32_16x16x32_bf16 v[60:63], v[84:87], v[164:167], v[60:63]
	v_mfma_f32_16x16x32_bf16 v[56:59], v[108:111], v[164:167], v[56:59]
	v_mfma_f32_16x16x32_bf16 v[44:47], v[84:87], v[172:175], v[44:47]
	v_mfma_f32_16x16x32_bf16 v[40:43], v[108:111], v[172:175], v[40:43]
	v_mfma_f32_16x16x32_bf16 v[28:31], v[84:87], v[180:183], v[28:31]
	v_mfma_f32_16x16x32_bf16 v[24:27], v[108:111], v[180:183], v[24:27]
	v_mfma_f32_16x16x32_bf16 v[12:15], v[84:87], v[202:205], v[12:15]
	v_mfma_f32_16x16x32_bf16 v[8:11], v[108:111], v[202:205], v[8:11]
	v_mfma_f32_16x16x32_bf16 v[52:55], v[128:131], v[160:163], v[52:55]
	v_mfma_f32_16x16x32_bf16 v[48:51], v[152:155], v[160:163], v[48:51]
	v_mfma_f32_16x16x32_bf16 v[36:39], v[128:131], v[168:171], v[36:39]
	v_mfma_f32_16x16x32_bf16 v[32:35], v[152:155], v[168:171], v[32:35]
	v_mfma_f32_16x16x32_bf16 v[20:23], v[128:131], v[176:179], v[20:23]
	v_mfma_f32_16x16x32_bf16 v[16:19], v[152:155], v[176:179], v[16:19]
	v_mfma_f32_16x16x32_bf16 v[4:7], v[128:131], v[198:201], v[4:7]
	v_mfma_f32_16x16x32_bf16 v[0:3], v[152:155], v[198:201], v[0:3]
	v_mfma_f32_16x16x32_bf16 v[52:55], v[136:139], v[164:167], v[52:55]
	v_mfma_f32_16x16x32_bf16 v[48:51], v[156:159], v[164:167], v[48:51]
	v_mfma_f32_16x16x32_bf16 v[36:39], v[136:139], v[172:175], v[36:39]
	v_mfma_f32_16x16x32_bf16 v[32:35], v[156:159], v[172:175], v[32:35]
	v_mfma_f32_16x16x32_bf16 v[20:23], v[136:139], v[180:183], v[20:23]
	v_mfma_f32_16x16x32_bf16 v[16:19], v[156:159], v[180:183], v[16:19]
	v_mfma_f32_16x16x32_bf16 v[4:7], v[136:139], v[202:205], v[4:7]
	v_mfma_f32_16x16x32_bf16 v[0:3], v[156:159], v[202:205], v[0:3]
	s_barrier
	s_add_u32 s16, s16, 0x10000
	s_addc_u32 s17, s17, 0
	s_add_u32 s66, s66, 0x10000
	s_addc_u32 s67, s67, 0
	s_cmp_ge_u32 s75, s53
	s_mov_b32 s18, s75
	s_cbranch_scc0 .LBB0_1322
	s_and_b64 vcc, exec, s[12:13]
	s_cbranch_vccz .LBB0_1325
	s_barrier

; #define PG8_STAGE(bufoff, gbase, voff) do { _Pragma("unroll") for (int _i = 0; _i < 2; ++_i) \
;         __builtin_amdgcn_global_load_lds((const unsigned*)((const char*)(gbase) + (voff)[_i]), (PG8_LAS unsigned*)(lds + (bufoff) + ldsw + _i * 8192), 16, 0, 0); } while (0)
; #define PG8_LDA(dst, b, h) do { _Pragma("unroll") for (int m = 0; m < 4; ++m) _Pragma("unroll") for (int k = 0; k < 2; ++k) dst[m][k] = *(const PG8_LAS bf16x8*)(lds + PG8_SA(b, h) + aoff + m * 2048 + k * 1024); } while (0)
; #define PG8_LDB(dst, b, h) do { _Pragma("unroll") for (int n = 0; n < 2; ++n) _Pragma("unroll") for (int k = 0; k < 2; ++k) dst[n][k] = *(const PG8_LAS bf16x8*)(lds + PG8_SB(b, h) + boff + n * 2048 + k * 1024); } while (0)
; #define PG8_MMA(ai, bj, At, Bt) do { __builtin_amdgcn_s_setprio(1); _Pragma("unroll") for (int m = 0; m < 4; ++m) _Pragma("unroll") for (int n = 0; n < 2; ++n) _Pragma("unroll") for (int k = 0; k < 2; ++k) \
;         acc[ai][bj][m][n] = __builtin_amdgcn_mfma_f32_16x16x32_bf16(Bt[n][k], At[m][k], acc[ai][bj][m][n], 0, 0, 0); __builtin_amdgcn_s_setprio(0); } while (0)
; #define PG8_BAR __builtin_amdgcn_s_barrier()
; template <class Epi, class Sched, bool ALIGN_EPI = false, bool SP2 = false>
; __device__ __forceinline__ void gemm_phase(PG8_LAS unsigned char* lds, const Gemm g, const Sched& S, const Epi& E) {
;     ...
;         const bool has_next = S.next(ui + 1, nxt);
;         const char* nA = has_next ? (const char*)g.A + (size_t)nxt.pm * tstep : cA; const char* nB = has_next ? (const char*)g.Bt + (size_t)nxt.pn * tstep : cB;
;         for (int t = 0; t < nt; t += 2) {
;             const bool last = (t == nt - 2);
;             const char* a1 = cA + (size_t)(t + 1) * kstep;
;             const char* a2 = last ? nA : cA + (size_t)(t + 2) * kstep; const char* b2 = last ? nB : cB + (size_t)(t + 2) * kstep;
;             const char* a3 = a2 + kstep; const char* b3 = b2 + kstep;
;             if (last && has_next) S.a_ready(nxt);
;             if constexpr (SP2) {
;             PG8_LDB(B0, 0, 0); PG8_LDB(B1, 0, 1); PG8_SCHED; PG8_LDA(At, 0, 0); PG8_STAGE(PG8_SA(1, 1), a1 + hstep, voffA);
;             PG8_WAIT_V(8); PG8_WAIT_L(0); PG8_BAR; PG8_MMA(0, 0, At, B0); PG8_MMA(0, 1, At, B1); PG8_BAR; PG8_SCHED;
;             PG8_LDA(At, 0, 1); PG8_STAGE(PG8_SB(0, 0), b2, voffB); PG8_STAGE(PG8_SB(0, 1), b2 + hstep, voffB); PG8_STAGE(PG8_SA(0, 0), a2, voffA);
.LBB0_1355:
	s_ashr_i32 s11, s10, 31
	s_lshl_b64 s[12:13], s[10:11], 19
	s_add_u32 s12, s22, s12
	s_addc_u32 s13, s23, s13
	s_and_b64 s[14:15], s[2:3], exec
	s_cselect_b32 s11, s13, s19
	s_cselect_b32 s40, s12, s18
	s_ashr_i32 s9, s8, 31
	s_lshl_b64 s[14:15], s[8:9], 19
	s_add_u32 s14, s27, s14
	s_addc_u32 s15, s28, s15
	s_and_b64 s[62:63], s[2:3], exec
	s_cselect_b32 s9, s15, s21
	s_cselect_b32 s61, s14, s20
	s_add_u32 s18, s18, 0xc000
	s_addc_u32 s19, s19, 0
	s_add_u32 s66, s20, 0x10000
	v_mov_b32_e32 v0, 0
	s_addc_u32 s67, s21, 0
	s_mov_b32 s68, -2
	v_add_u32_e32 v246, 0x10000, v162
	s_add_u32 s20, s18, 0x4000
	s_addc_u32 s21, s19, 0
	s_cmp_eq_u32 s68, 12
	s_cselect_b32 s64, s40, s20
	s_cselect_b32 s65, s11, s21
	s_cselect_b32 s62, s61, s66
	s_cselect_b32 s63, s9, s67
	s_add_u32 s20, s64, 0x8000
	s_addc_u32 s21, s65, 0
	ds_read_b128 v[128:131], v246
	ds_read_b128 v[132:135], v246 offset:1024
	ds_read_b128 v[136:139], v246 offset:2048
	ds_read_b128 v[140:143], v246 offset:3072
	ds_read_b128 v[156:159], v246 offset:16384
	ds_read_b128 v[164:167], v246 offset:17408
	ds_read_b128 v[168:171], v246 offset:18432
	ds_read_b128 v[172:175], v246 offset:19456
	s_add_i32 m0, s37, 0xc000
	ds_read_b128 v[176:179], v163
	ds_read_b128 v[180:183], v163 offset:1024
	ds_read_b128 v[184:187], v163 offset:2048
	ds_read_b128 v[188:191], v163 offset:3072
	ds_read_b128 v[192:195], v163 offset:4096
	ds_read_b128 v[196:199], v163 offset:5120
	ds_read_b128 v[200:203], v163 offset:6144
	ds_read_b128 v[204:207], v163 offset:7168
	global_load_lds_dwordx4 v152, s[18:19]
	s_add_i32 m0, s37, 0xe000
	s_nop 0
	global_load_lds_dwordx4 v154, s[18:19]
	s_waitcnt vmcnt(8) lgkmcnt(0)
	s_barrier
	v_mfma_f32_16x16x32_bf16 v[124:127], v[128:131], v[176:179], 0
	v_mfma_f32_16x16x32_bf16 v[120:123], v[136:139], v[176:179], 0
	v_mfma_f32_16x16x32_bf16 v[108:111], v[128:131], v[184:187], 0
	v_mfma_f32_16x16x32_bf16 v[104:107], v[136:139], v[184:187], 0
	v_mfma_f32_16x16x32_bf16 v[92:95], v[128:131], v[192:195], 0
	v_mfma_f32_16x16x32_bf16 v[88:91], v[136:139], v[192:195], 0
	v_mfma_f32_16x16x32_bf16 v[76:79], v[128:131], v[200:203], 0
	v_mfma_f32_16x16x32_bf16 v[72:75], v[136:139], v[200:203], 0
	v_mfma_f32_16x16x32_bf16 v[124:127], v[132:135], v[180:183], v[124:127]
	v_mfma_f32_16x16x32_bf16 v[120:123], v[140:143], v[180:183], v[120:123]
	v_mfma_f32_16x16x32_bf16 v[108:111], v[132:135], v[188:191], v[108:111]
	v_mfma_f32_16x16x32_bf16 v[104:107], v[140:143], v[188:191], v[104:107]
	v_mfma_f32_16x16x32_bf16 v[92:95], v[132:135], v[196:199], v[92:95]
	v_mfma_f32_16x16x32_bf16 v[88:91], v[140:143], v[196:199], v[88:91]
	v_mfma_f32_16x16x32_bf16 v[76:79], v[132:135], v[204:207], v[76:79]
	v_mfma_f32_16x16x32_bf16 v[72:75], v[140:143], v[204:207], v[72:75]
	v_mfma_f32_16x16x32_bf16 v[116:119], v[156:159], v[176:179], 0
	v_mfma_f32_16x16x32_bf16 v[112:115], v[168:171], v[176:179], 0
	v_mfma_f32_16x16x32_bf16 v[100:103], v[156:159], v[184:187], 0
	v_mfma_f32_16x16x32_bf16 v[96:99], v[168:171], v[184:187], 0
	v_mfma_f32_16x16x32_bf16 v[84:87], v[156:159], v[192:195], 0
	v_mfma_f32_16x16x32_bf16 v[80:83], v[168:171], v[192:195], 0
	v_mfma_f32_16x16x32_bf16 v[68:71], v[156:159], v[200:203], 0
	v_mfma_f32_16x16x32_bf16 v[64:67], v[168:171], v[200:203], 0
	v_mfma_f32_16x16x32_bf16 v[116:119], v[164:167], v[180:183], v[116:119]
	v_mfma_f32_16x16x32_bf16 v[112:115], v[172:175], v[180:183], v[112:115]
	v_mfma_f32_16x16x32_bf16 v[100:103], v[164:167], v[188:191], v[100:103]
	v_mfma_f32_16x16x32_bf16 v[96:99], v[172:175], v[188:191], v[96:99]
	v_mfma_f32_16x16x32_bf16 v[84:87], v[164:167], v[196:199], v[84:87]
	v_mfma_f32_16x16x32_bf16 v[80:83], v[172:175], v[196:199], v[80:83]
	v_mfma_f32_16x16x32_bf16 v[68:71], v[164:167], v[204:207], v[68:71]
	v_mfma_f32_16x16x32_bf16 v[64:67], v[172:175], v[204:207], v[64:67]
	s_barrier
	s_add_i32 m0, s30, 0x10000
	ds_read_b128 v[176:179], v163 offset:16384
	ds_read_b128 v[180:183], v163 offset:17408
	ds_read_b128 v[184:187], v163 offset:18432
	ds_read_b128 v[188:191], v163 offset:19456
	ds_read_b128 v[192:195], v163 offset:20480
	ds_read_b128 v[196:199], v163 offset:21504
	ds_read_b128 v[200:203], v163 offset:22528
	ds_read_b128 v[204:207], v163 offset:23552
	global_load_lds_dwordx4 v148, s[62:63]
	s_add_i32 m0, s30, 0x12000
	s_add_u32 s70, s62, 0x4000
	s_addc_u32 s71, s63, 0
	global_load_lds_dwordx4 v144, s[62:63]
	s_add_i32 m0, s30, 0x14000
	s_nop 0
	global_load_lds_dwordx4 v148, s[70:71]
	s_add_i32 m0, s30, 0x16000
	s_nop 0
	global_load_lds_dwordx4 v144, s[70:71]
	s_mov_b32 m0, s37
	s_nop 0
	global_load_lds_dwordx4 v150, s[64:65]
	s_mov_b32 m0, s39
	s_nop 0
	global_load_lds_dwordx4 v146, s[64:65]
	s_waitcnt vmcnt(8) lgkmcnt(0)
	s_barrier
; #define PG8_STAGE(bufoff, gbase, voff) do { _Pragma("unroll") for (int _i = 0; _i < 2; ++_i) \
;         __builtin_amdgcn_global_load_lds((const unsigned*)((const char*)(gbase) + (voff)[_i]), (PG8_LAS unsigned*)(lds + (bufoff) + ldsw + _i * 8192), 16, 0, 0); } while (0)
; #define PG8_LDA(dst, b, h) do { _Pragma("unroll") for (int m = 0; m < 4; ++m) _Pragma("unroll") for (int k = 0; k < 2; ++k) dst[m][k] = *(const PG8_LAS bf16x8*)(lds + PG8_SA(b, h) + aoff + m * 2048 + k * 1024); } while (0)
; #define PG8_LDB(dst, b, h) do { _Pragma("unroll") for (int n = 0; n < 2; ++n) _Pragma("unroll") for (int k = 0; k < 2; ++k) dst[n][k] = *(const PG8_LAS bf16x8*)(lds + PG8_SB(b, h) + boff + n * 2048 + k * 1024); } while (0)
; #define PG8_MMA(ai, bj, At, Bt) do { __builtin_amdgcn_s_setprio(1); _Pragma("unroll") for (int m = 0; m < 4; ++m) _Pragma("unroll") for (int n = 0; n < 2; ++n) _Pragma("unroll") for (int k = 0; k < 2; ++k) \
;         acc[ai][bj][m][n] = __builtin_amdgcn_mfma_f32_16x16x32_bf16(Bt[n][k], At[m][k], acc[ai][bj][m][n], 0, 0, 0); __builtin_amdgcn_s_setprio(0); } while (0)
; #define PG8_WAIT_V(n) asm volatile("s_waitcnt vmcnt(" #n ")" ::: "memory")
; #define PG8_WAIT_L(n) asm volatile("s_waitcnt lgkmcnt(" #n ")" ::: "memory")
; #define PG8_BAR __builtin_amdgcn_s_barrier()
; #define PG8_SCHED __builtin_amdgcn_sched_barrier(0)
; template <class Epi, class Sched, bool ALIGN_EPI = false, bool SP2 = false>
; __device__ __forceinline__ void gemm_phase(PG8_LAS unsigned char* lds, const Gemm g, const Sched& S, const Epi& E) {
;     ...
;             PG8_WAIT_V(8); PG8_WAIT_L(0); PG8_BAR; PG8_MMA(0, 0, At, B0); PG8_MMA(0, 1, At, B1); PG8_BAR; PG8_SCHED;
;             PG8_LDA(At, 0, 1); PG8_STAGE(PG8_SB(0, 0), b2, voffB); PG8_STAGE(PG8_SB(0, 1), b2 + hstep, voffB); PG8_STAGE(PG8_SA(0, 0), a2, voffA);
;             PG8_WAIT_V(8); PG8_WAIT_L(0); PG8_BAR; PG8_MMA(1, 0, At, B0); PG8_MMA(1, 1, At, B1); PG8_BAR; PG8_SCHED;
;             PG8_LDB(B0, 1, 0); PG8_LDB(B1, 1, 1); PG8_SCHED; PG8_LDA(At, 1, 0); PG8_STAGE(PG8_SA(0, 1), a2 + hstep, voffA);
;             PG8_WAIT_V(8); PG8_WAIT_L(0); PG8_BAR; PG8_MMA(0, 0, At, B0); PG8_MMA(0, 1, At, B1); PG8_BAR; PG8_SCHED;
	v_mfma_f32_16x16x32_bf16 v[60:63], v[128:131], v[176:179], 0
	v_mfma_f32_16x16x32_bf16 v[56:59], v[136:139], v[176:179], 0
	v_mfma_f32_16x16x32_bf16 v[44:47], v[128:131], v[184:187], 0
	v_mfma_f32_16x16x32_bf16 v[40:43], v[136:139], v[184:187], 0
	v_mfma_f32_16x16x32_bf16 v[28:31], v[128:131], v[192:195], 0
	v_mfma_f32_16x16x32_bf16 v[24:27], v[136:139], v[192:195], 0
	v_mfma_f32_16x16x32_bf16 v[12:15], v[128:131], v[200:203], 0
	v_mfma_f32_16x16x32_bf16 v[8:11], v[136:139], v[200:203], 0
	v_mfma_f32_16x16x32_bf16 v[60:63], v[132:135], v[180:183], v[60:63]
	v_mfma_f32_16x16x32_bf16 v[56:59], v[140:143], v[180:183], v[56:59]
	v_mfma_f32_16x16x32_bf16 v[44:47], v[132:135], v[188:191], v[44:47]
	v_mfma_f32_16x16x32_bf16 v[40:43], v[140:143], v[188:191], v[40:43]
	v_mfma_f32_16x16x32_bf16 v[28:31], v[132:135], v[196:199], v[28:31]
	v_mfma_f32_16x16x32_bf16 v[24:27], v[140:143], v[196:199], v[24:27]
	v_mfma_f32_16x16x32_bf16 v[12:15], v[132:135], v[204:207], v[12:15]
	v_mfma_f32_16x16x32_bf16 v[8:11], v[140:143], v[204:207], v[8:11]
	v_mfma_f32_16x16x32_bf16 v[52:55], v[156:159], v[176:179], 0
	v_mfma_f32_16x16x32_bf16 v[48:51], v[168:171], v[176:179], 0
	v_mfma_f32_16x16x32_bf16 v[36:39], v[156:159], v[184:187], 0
	v_mfma_f32_16x16x32_bf16 v[32:35], v[168:171], v[184:187], 0
	v_mfma_f32_16x16x32_bf16 v[20:23], v[156:159], v[192:195], 0
	v_mfma_f32_16x16x32_bf16 v[16:19], v[168:171], v[192:195], 0
	v_mfma_f32_16x16x32_bf16 v[4:7], v[156:159], v[200:203], 0
	v_mfma_f32_16x16x32_bf16 v[0:3], v[168:171], v[200:203], 0
	v_mfma_f32_16x16x32_bf16 v[52:55], v[164:167], v[180:183], v[52:55]
	v_mfma_f32_16x16x32_bf16 v[48:51], v[172:175], v[180:183], v[48:51]
	v_mfma_f32_16x16x32_bf16 v[36:39], v[164:167], v[188:191], v[36:39]
	v_mfma_f32_16x16x32_bf16 v[32:35], v[172:175], v[188:191], v[32:35]
	v_mfma_f32_16x16x32_bf16 v[20:23], v[164:167], v[196:199], v[20:23]
	v_mfma_f32_16x16x32_bf16 v[16:19], v[172:175], v[196:199], v[16:19]
	v_mfma_f32_16x16x32_bf16 v[4:7], v[164:167], v[204:207], v[4:7]
	v_mfma_f32_16x16x32_bf16 v[0:3], v[172:175], v[204:207], v[0:3]
	s_barrier
	ds_read_b128 v[128:131], v246 offset:32768
	ds_read_b128 v[132:135], v246 offset:33792
	ds_read_b128 v[136:139], v246 offset:34816
	ds_read_b128 v[140:143], v246 offset:35840
	ds_read_b128 v[156:159], v246 offset:49152
	ds_read_b128 v[164:167], v246 offset:50176
	ds_read_b128 v[168:171], v246 offset:51200
	ds_read_b128 v[172:175], v246 offset:52224
	s_add_u32 s64, s64, 0x4000
	s_addc_u32 s65, s65, 0
	s_mov_b32 m0, s41
	ds_read_b128 v[176:179], v163 offset:32768
	ds_read_b128 v[180:183], v163 offset:33792
	ds_read_b128 v[184:187], v163 offset:34816
	ds_read_b128 v[188:191], v163 offset:35840
	ds_read_b128 v[192:195], v163 offset:36864
	ds_read_b128 v[196:199], v163 offset:37888
	ds_read_b128 v[200:203], v163 offset:38912
	ds_read_b128 v[204:207], v163 offset:39936
	global_load_lds_dwordx4 v150, s[64:65]
	s_mov_b32 m0, s42
	s_nop 0
	global_load_lds_dwordx4 v146, s[64:65]
	s_waitcnt vmcnt(8) lgkmcnt(0)
	s_barrier
	v_mfma_f32_16x16x32_bf16 v[124:127], v[128:131], v[176:179], v[124:127]
	v_mfma_f32_16x16x32_bf16 v[120:123], v[136:139], v[176:179], v[120:123]
	v_mfma_f32_16x16x32_bf16 v[108:111], v[128:131], v[184:187], v[108:111]
	v_mfma_f32_16x16x32_bf16 v[104:107], v[136:139], v[184:187], v[104:107]
	v_mfma_f32_16x16x32_bf16 v[92:95], v[128:131], v[192:195], v[92:95]
	v_mfma_f32_16x16x32_bf16 v[88:91], v[136:139], v[192:195], v[88:91]
	v_mfma_f32_16x16x32_bf16 v[76:79], v[128:131], v[200:203], v[76:79]
	v_mfma_f32_16x16x32_bf16 v[72:75], v[136:139], v[200:203], v[72:75]
	v_mfma_f32_16x16x32_bf16 v[124:127], v[132:135], v[180:183], v[124:127]
	v_mfma_f32_16x16x32_bf16 v[120:123], v[140:143], v[180:183], v[120:123]
	v_mfma_f32_16x16x32_bf16 v[108:111], v[132:135], v[188:191], v[108:111]
	v_mfma_f32_16x16x32_bf16 v[104:107], v[140:143], v[188:191], v[104:107]
	v_mfma_f32_16x16x32_bf16 v[92:95], v[132:135], v[196:199], v[92:95]
	v_mfma_f32_16x16x32_bf16 v[88:91], v[140:143], v[196:199], v[88:91]
	v_mfma_f32_16x16x32_bf16 v[76:79], v[132:135], v[204:207], v[76:79]
	v_mfma_f32_16x16x32_bf16 v[72:75], v[140:143], v[204:207], v[72:75]
	v_mfma_f32_16x16x32_bf16 v[116:119], v[156:159], v[176:179], v[116:119]
	v_mfma_f32_16x16x32_bf16 v[112:115], v[168:171], v[176:179], v[112:115]
	v_mfma_f32_16x16x32_bf16 v[100:103], v[156:159], v[184:187], v[100:103]
	v_mfma_f32_16x16x32_bf16 v[96:99], v[168:171], v[184:187], v[96:99]
	v_mfma_f32_16x16x32_bf16 v[84:87], v[156:159], v[192:195], v[84:87]
	v_mfma_f32_16x16x32_bf16 v[80:83], v[168:171], v[192:195], v[80:83]
	v_mfma_f32_16x16x32_bf16 v[68:71], v[156:159], v[200:203], v[68:71]
	v_mfma_f32_16x16x32_bf16 v[64:67], v[168:171], v[200:203], v[64:67]
	v_mfma_f32_16x16x32_bf16 v[116:119], v[164:167], v[180:183], v[116:119]
	v_mfma_f32_16x16x32_bf16 v[112:115], v[172:175], v[180:183], v[112:115]
	v_mfma_f32_16x16x32_bf16 v[100:103], v[164:167], v[188:191], v[100:103]
	v_mfma_f32_16x16x32_bf16 v[96:99], v[172:175], v[188:191], v[96:99]
	v_mfma_f32_16x16x32_bf16 v[84:87], v[164:167], v[196:199], v[84:87]
	v_mfma_f32_16x16x32_bf16 v[80:83], v[172:175], v[196:199], v[80:83]
	v_mfma_f32_16x16x32_bf16 v[68:71], v[164:167], v[204:207], v[68:71]
	v_mfma_f32_16x16x32_bf16 v[64:67], v[172:175], v[204:207], v[64:67]
	s_barrier
; #define PG8_STAGE(bufoff, gbase, voff) do { _Pragma("unroll") for (int _i = 0; _i < 2; ++_i) \
;         __builtin_amdgcn_global_load_lds((const unsigned*)((const char*)(gbase) + (voff)[_i]), (PG8_LAS unsigned*)(lds + (bufoff) + ldsw + _i * 8192), 16, 0, 0); } while (0)
; #define PG8_LDA(dst, b, h) do { _Pragma("unroll") for (int m = 0; m < 4; ++m) _Pragma("unroll") for (int k = 0; k < 2; ++k) dst[m][k] = *(const PG8_LAS bf16x8*)(lds + PG8_SA(b, h) + aoff + m * 2048 + k * 1024); } while (0)
; #define PG8_LDB(dst, b, h) do { _Pragma("unroll") for (int n = 0; n < 2; ++n) _Pragma("unroll") for (int k = 0; k < 2; ++k) dst[n][k] = *(const PG8_LAS bf16x8*)(lds + PG8_SB(b, h) + boff + n * 2048 + k * 1024); } while (0)
; template <class Epi, class Sched, bool ALIGN_EPI = false, bool SP2 = false>
; __device__ __forceinline__ void gemm_phase(PG8_LAS unsigned char* lds, const Gemm g, const Sched& S, const Epi& E) {
;     ...
;         for (int t = 0; t < nt; t += 2) {
;             const bool last = (t == nt - 2);
;             const char* a1 = cA + (size_t)(t + 1) * kstep;
;             const char* a2 = last ? nA : cA + (size_t)(t + 2) * kstep; const char* b2 = last ? nB : cB + (size_t)(t + 2) * kstep;
;             const char* a3 = a2 + kstep; const char* b3 = b2 + kstep;
;             if (last && has_next) S.a_ready(nxt);
;             if constexpr (SP2) {
;             PG8_LDB(B0, 0, 0); PG8_LDB(B1, 0, 1); PG8_SCHED; PG8_LDA(At, 0, 0); PG8_STAGE(PG8_SA(1, 1), a1 + hstep, voffA);
;             PG8_WAIT_V(8); PG8_WAIT_L(0); PG8_BAR; PG8_MMA(0, 0, At, B0); PG8_MMA(0, 1, At, B1); PG8_BAR; PG8_SCHED;
;             PG8_LDA(At, 0, 1); PG8_STAGE(PG8_SB(0, 0), b2, voffB); PG8_STAGE(PG8_SB(0, 1), b2 + hstep, voffB); PG8_STAGE(PG8_SA(0, 0), a2, voffA);
;             PG8_WAIT_V(8); PG8_WAIT_L(0); PG8_BAR; PG8_MMA(1, 0, At, B0); PG8_MMA(1, 1, At, B1); PG8_BAR; PG8_SCHED;
;             PG8_LDB(B0, 1, 0); PG8_LDB(B1, 1, 1); PG8_SCHED; PG8_LDA(At, 1, 0); PG8_STAGE(PG8_SA(0, 1), a2 + hstep, voffA);
;             PG8_WAIT_V(8); PG8_WAIT_L(0); PG8_BAR; PG8_MMA(0, 0, At, B0); PG8_MMA(0, 1, At, B1); PG8_BAR; PG8_SCHED;
;             PG8_LDA(At, 1, 1); PG8_STAGE(PG8_SB(1, 0), b3, voffB); PG8_STAGE(PG8_SB(1, 1), b3 + hstep, voffB); PG8_STAGE(PG8_SA(1, 0), a3, voffA);
;             PG8_WAIT_V(8); PG8_WAIT_L(0); PG8_BAR; PG8_MMA(1, 0, At, B0); PG8_MMA(1, 1, At, B1); PG8_BAR; PG8_SCHED;
	s_add_u32 s64, s62, 0x8000
	s_addc_u32 s65, s63, 0
	s_add_i32 m0, s30, 0x18000
	ds_read_b128 v[176:179], v163 offset:49152
	ds_read_b128 v[180:183], v163 offset:50176
	ds_read_b128 v[184:187], v163 offset:51200
	ds_read_b128 v[188:191], v163 offset:52224
	ds_read_b128 v[192:195], v163 offset:53248
	ds_read_b128 v[196:199], v163 offset:54272
	ds_read_b128 v[200:203], v163 offset:55296
	ds_read_b128 v[204:207], v163 offset:56320
	global_load_lds_dwordx4 v148, s[64:65]
	s_add_i32 m0, s30, 0x1a000
	s_add_u32 s62, s62, 0xc000
	s_addc_u32 s63, s63, 0
	global_load_lds_dwordx4 v144, s[64:65]
	s_add_i32 m0, s30, 0x1c000
	s_nop 0
	global_load_lds_dwordx4 v148, s[62:63]
	s_add_i32 m0, s30, 0x1e000
	s_nop 0
	global_load_lds_dwordx4 v144, s[62:63]
	s_mov_b32 m0, s54
	s_nop 0
	global_load_lds_dwordx4 v150, s[20:21]
	s_mov_b32 m0, s55
	s_nop 0
	global_load_lds_dwordx4 v146, s[20:21]
	s_waitcnt vmcnt(8) lgkmcnt(0)
	s_barrier
	v_mfma_f32_16x16x32_bf16 v[60:63], v[128:131], v[176:179], v[60:63]
	v_mfma_f32_16x16x32_bf16 v[56:59], v[136:139], v[176:179], v[56:59]
	v_mfma_f32_16x16x32_bf16 v[44:47], v[128:131], v[184:187], v[44:47]
	v_mfma_f32_16x16x32_bf16 v[40:43], v[136:139], v[184:187], v[40:43]
	v_mfma_f32_16x16x32_bf16 v[28:31], v[128:131], v[192:195], v[28:31]
	v_mfma_f32_16x16x32_bf16 v[24:27], v[136:139], v[192:195], v[24:27]
	v_mfma_f32_16x16x32_bf16 v[12:15], v[128:131], v[200:203], v[12:15]
	v_mfma_f32_16x16x32_bf16 v[8:11], v[136:139], v[200:203], v[8:11]
	v_mfma_f32_16x16x32_bf16 v[60:63], v[132:135], v[180:183], v[60:63]
	v_mfma_f32_16x16x32_bf16 v[56:59], v[140:143], v[180:183], v[56:59]
	v_mfma_f32_16x16x32_bf16 v[44:47], v[132:135], v[188:191], v[44:47]
	v_mfma_f32_16x16x32_bf16 v[40:43], v[140:143], v[188:191], v[40:43]
	v_mfma_f32_16x16x32_bf16 v[28:31], v[132:135], v[196:199], v[28:31]
	v_mfma_f32_16x16x32_bf16 v[24:27], v[140:143], v[196:199], v[24:27]
	v_mfma_f32_16x16x32_bf16 v[12:15], v[132:135], v[204:207], v[12:15]
	v_mfma_f32_16x16x32_bf16 v[8:11], v[140:143], v[204:207], v[8:11]
	v_mfma_f32_16x16x32_bf16 v[52:55], v[156:159], v[176:179], v[52:55]
	v_mfma_f32_16x16x32_bf16 v[48:51], v[168:171], v[176:179], v[48:51]
	v_mfma_f32_16x16x32_bf16 v[36:39], v[156:159], v[184:187], v[36:39]
	v_mfma_f32_16x16x32_bf16 v[32:35], v[168:171], v[184:187], v[32:35]
	v_mfma_f32_16x16x32_bf16 v[20:23], v[156:159], v[192:195], v[20:23]
	v_mfma_f32_16x16x32_bf16 v[16:19], v[168:171], v[192:195], v[16:19]
	v_mfma_f32_16x16x32_bf16 v[4:7], v[156:159], v[200:203], v[4:7]
	v_mfma_f32_16x16x32_bf16 v[0:3], v[168:171], v[200:203], v[0:3]
	v_mfma_f32_16x16x32_bf16 v[52:55], v[164:167], v[180:183], v[52:55]
	v_mfma_f32_16x16x32_bf16 v[48:51], v[172:175], v[180:183], v[48:51]
	v_mfma_f32_16x16x32_bf16 v[36:39], v[164:167], v[188:191], v[36:39]
	v_mfma_f32_16x16x32_bf16 v[32:35], v[172:175], v[188:191], v[32:35]
	v_mfma_f32_16x16x32_bf16 v[20:23], v[164:167], v[196:199], v[20:23]
	v_mfma_f32_16x16x32_bf16 v[16:19], v[172:175], v[196:199], v[16:19]
	v_mfma_f32_16x16x32_bf16 v[4:7], v[164:167], v[204:207], v[4:7]
	v_mfma_f32_16x16x32_bf16 v[0:3], v[172:175], v[204:207], v[0:3]
	s_barrier
	s_add_i32 s68, s68, 2
	s_add_u32 s18, s18, 0x10000
	s_addc_u32 s19, s19, 0
	s_add_u32 s66, s66, 0x10000
	s_addc_u32 s67, s67, 0
	s_cmp_gt_u32 s68, 13
.LBB0_1356:
	s_add_u32 s20, s18, 0x4000
	s_addc_u32 s21, s19, 0
	s_cmp_eq_u32 s68, 12
	s_cselect_b32 s64, s40, s20
	s_cselect_b32 s65, s11, s21
	s_cselect_b32 s62, s61, s66
	s_cselect_b32 s63, s9, s67
	s_add_u32 s20, s64, 0x8000
	s_addc_u32 s21, s65, 0
	ds_read_b128 v[128:131], v246
	ds_read_b128 v[132:135], v246 offset:1024
	ds_read_b128 v[136:139], v246 offset:2048
	ds_read_b128 v[140:143], v246 offset:3072
	ds_read_b128 v[156:159], v246 offset:16384
	ds_read_b128 v[164:167], v246 offset:17408
	ds_read_b128 v[168:171], v246 offset:18432
	ds_read_b128 v[172:175], v246 offset:19456
	s_add_i32 m0, s37, 0xc000
	ds_read_b128 v[176:179], v163
	ds_read_b128 v[180:183], v163 offset:1024
	ds_read_b128 v[184:187], v163 offset:2048
	ds_read_b128 v[188:191], v163 offset:3072
	ds_read_b128 v[192:195], v163 offset:4096
	ds_read_b128 v[196:199], v163 offset:5120
	ds_read_b128 v[200:203], v163 offset:6144
	ds_read_b128 v[204:207], v163 offset:7168
	global_load_lds_dwordx4 v152, s[18:19]
	s_add_i32 m0, s37, 0xe000
	s_nop 0
	global_load_lds_dwordx4 v154, s[18:19]
	s_waitcnt vmcnt(8) lgkmcnt(0)
	s_barrier
	v_mfma_f32_16x16x32_bf16 v[124:127], v[128:131], v[176:179], v[124:127]
	v_mfma_f32_16x16x32_bf16 v[120:123], v[136:139], v[176:179], v[120:123]
	v_mfma_f32_16x16x32_bf16 v[108:111], v[128:131], v[184:187], v[108:111]
	v_mfma_f32_16x16x32_bf16 v[104:107], v[136:139], v[184:187], v[104:107]
	v_mfma_f32_16x16x32_bf16 v[92:95], v[128:131], v[192:195], v[92:95]
	v_mfma_f32_16x16x32_bf16 v[88:91], v[136:139], v[192:195], v[88:91]
	v_mfma_f32_16x16x32_bf16 v[76:79], v[128:131], v[200:203], v[76:79]
	v_mfma_f32_16x16x32_bf16 v[72:75], v[136:139], v[200:203], v[72:75]
	v_mfma_f32_16x16x32_bf16 v[124:127], v[132:135], v[180:183], v[124:127]
	v_mfma_f32_16x16x32_bf16 v[120:123], v[140:143], v[180:183], v[120:123]
	v_mfma_f32_16x16x32_bf16 v[108:111], v[132:135], v[188:191], v[108:111]
	v_mfma_f32_16x16x32_bf16 v[104:107], v[140:143], v[188:191], v[104:107]
	v_mfma_f32_16x16x32_bf16 v[92:95], v[132:135], v[196:199], v[92:95]
	v_mfma_f32_16x16x32_bf16 v[88:91], v[140:143], v[196:199], v[88:91]
	v_mfma_f32_16x16x32_bf16 v[76:79], v[132:135], v[204:207], v[76:79]
	v_mfma_f32_16x16x32_bf16 v[72:75], v[140:143], v[204:207], v[72:75]
	v_mfma_f32_16x16x32_bf16 v[116:119], v[156:159], v[176:179], v[116:119]
	v_mfma_f32_16x16x32_bf16 v[112:115], v[168:171], v[176:179], v[112:115]
	v_mfma_f32_16x16x32_bf16 v[100:103], v[156:159], v[184:187], v[100:103]
	v_mfma_f32_16x16x32_bf16 v[96:99], v[168:171], v[184:187], v[96:99]
	v_mfma_f32_16x16x32_bf16 v[84:87], v[156:159], v[192:195], v[84:87]
	v_mfma_f32_16x16x32_bf16 v[80:83], v[168:171], v[192:195], v[80:83]
	v_mfma_f32_16x16x32_bf16 v[68:71], v[156:159], v[200:203], v[68:71]
	v_mfma_f32_16x16x32_bf16 v[64:67], v[168:171], v[200:203], v[64:67]
	v_mfma_f32_16x16x32_bf16 v[116:119], v[164:167], v[180:183], v[116:119]
	v_mfma_f32_16x16x32_bf16 v[112:115], v[172:175], v[180:183], v[112:115]
	v_mfma_f32_16x16x32_bf16 v[100:103], v[164:167], v[188:191], v[100:103]
	v_mfma_f32_16x16x32_bf16 v[96:99], v[172:175], v[188:191], v[96:99]
	v_mfma_f32_16x16x32_bf16 v[84:87], v[164:167], v[196:199], v[84:87]
	v_mfma_f32_16x16x32_bf16 v[80:83], v[172:175], v[196:199], v[80:83]
	v_mfma_f32_16x16x32_bf16 v[68:71], v[164:167], v[204:207], v[68:71]
	v_mfma_f32_16x16x32_bf16 v[64:67], v[172:175], v[204:207], v[64:67]
	s_barrier
; #define PG8_STAGE(bufoff, gbase, voff) do { _Pragma("unroll") for (int _i = 0; _i < 2; ++_i) \
;         __builtin_amdgcn_global_load_lds((const unsigned*)((const char*)(gbase) + (voff)[_i]), (PG8_LAS unsigned*)(lds + (bufoff) + ldsw + _i * 8192), 16, 0, 0); } while (0)
; #define PG8_LDA(dst, b, h) do { _Pragma("unroll") for (int m = 0; m < 4; ++m) _Pragma("unroll") for (int k = 0; k < 2; ++k) dst[m][k] = *(const PG8_LAS bf16x8*)(lds + PG8_SA(b, h) + aoff + m * 2048 + k * 1024); } while (0)
; #define PG8_LDB(dst, b, h) do { _Pragma("unroll") for (int n = 0; n < 2; ++n) _Pragma("unroll") for (int k = 0; k < 2; ++k) dst[n][k] = *(const PG8_LAS bf16x8*)(lds + PG8_SB(b, h) + boff + n * 2048 + k * 1024); } while (0)
; #define PG8_MMA(ai, bj, At, Bt) do { __builtin_amdgcn_s_setprio(1); _Pragma("unroll") for (int m = 0; m < 4; ++m) _Pragma("unroll") for (int n = 0; n < 2; ++n) _Pragma("unroll") for (int k = 0; k < 2; ++k) \
;         acc[ai][bj][m][n] = __builtin_amdgcn_mfma_f32_16x16x32_bf16(Bt[n][k], At[m][k], acc[ai][bj][m][n], 0, 0, 0); __builtin_amdgcn_s_setprio(0); } while (0)
; #define PG8_WAIT_V(n) asm volatile("s_waitcnt vmcnt(" #n ")" ::: "memory")
; #define PG8_WAIT_L(n) asm volatile("s_waitcnt lgkmcnt(" #n ")" ::: "memory")
; #define PG8_BAR __builtin_amdgcn_s_barrier()
; #define PG8_SCHED __builtin_amdgcn_sched_barrier(0)
; template <class Epi, class Sched, bool ALIGN_EPI = false, bool SP2 = false>
; __device__ __forceinline__ void gemm_phase(PG8_LAS unsigned char* lds, const Gemm g, const Sched& S, const Epi& E) {
;     ...
;             PG8_WAIT_V(8); PG8_WAIT_L(0); PG8_BAR; PG8_MMA(0, 0, At, B0); PG8_MMA(0, 1, At, B1); PG8_BAR; PG8_SCHED;
;             PG8_LDA(At, 0, 1); PG8_STAGE(PG8_SB(0, 0), b2, voffB); PG8_STAGE(PG8_SB(0, 1), b2 + hstep, voffB); PG8_STAGE(PG8_SA(0, 0), a2, voffA);
;             PG8_WAIT_V(8); PG8_WAIT_L(0); PG8_BAR; PG8_MMA(1, 0, At, B0); PG8_MMA(1, 1, At, B1); PG8_BAR; PG8_SCHED;
;             PG8_LDB(B0, 1, 0); PG8_LDB(B1, 1, 1); PG8_SCHED; PG8_LDA(At, 1, 0); PG8_STAGE(PG8_SA(0, 1), a2 + hstep, voffA);
	s_add_i32 m0, s30, 0x10000
	ds_read_b128 v[176:179], v163 offset:16384
	ds_read_b128 v[180:183], v163 offset:17408
	ds_read_b128 v[184:187], v163 offset:18432
	ds_read_b128 v[188:191], v163 offset:19456
	ds_read_b128 v[192:195], v163 offset:20480
	ds_read_b128 v[196:199], v163 offset:21504
	ds_read_b128 v[200:203], v163 offset:22528
	ds_read_b128 v[204:207], v163 offset:23552
	global_load_lds_dwordx4 v148, s[62:63]
	s_add_i32 m0, s30, 0x12000
	s_add_u32 s70, s62, 0x4000
	s_addc_u32 s71, s63, 0
	global_load_lds_dwordx4 v144, s[62:63]
	s_add_i32 m0, s30, 0x14000
	s_nop 0
	global_load_lds_dwordx4 v148, s[70:71]
	s_add_i32 m0, s30, 0x16000
	s_nop 0
	global_load_lds_dwordx4 v144, s[70:71]
	s_mov_b32 m0, s37
	s_nop 0
	global_load_lds_dwordx4 v150, s[64:65]
	s_mov_b32 m0, s39
	s_nop 0
	global_load_lds_dwordx4 v146, s[64:65]
	s_waitcnt vmcnt(8) lgkmcnt(0)
	s_barrier
	v_mfma_f32_16x16x32_bf16 v[60:63], v[128:131], v[176:179], v[60:63]
	v_mfma_f32_16x16x32_bf16 v[56:59], v[136:139], v[176:179], v[56:59]
	v_mfma_f32_16x16x32_bf16 v[44:47], v[128:131], v[184:187], v[44:47]
	v_mfma_f32_16x16x32_bf16 v[40:43], v[136:139], v[184:187], v[40:43]
	v_mfma_f32_16x16x32_bf16 v[28:31], v[128:131], v[192:195], v[28:31]
	v_mfma_f32_16x16x32_bf16 v[24:27], v[136:139], v[192:195], v[24:27]
	v_mfma_f32_16x16x32_bf16 v[12:15], v[128:131], v[200:203], v[12:15]
	v_mfma_f32_16x16x32_bf16 v[8:11], v[136:139], v[200:203], v[8:11]
	v_mfma_f32_16x16x32_bf16 v[60:63], v[132:135], v[180:183], v[60:63]
	v_mfma_f32_16x16x32_bf16 v[56:59], v[140:143], v[180:183], v[56:59]
	v_mfma_f32_16x16x32_bf16 v[44:47], v[132:135], v[188:191], v[44:47]
	v_mfma_f32_16x16x32_bf16 v[40:43], v[140:143], v[188:191], v[40:43]
	v_mfma_f32_16x16x32_bf16 v[28:31], v[132:135], v[196:199], v[28:31]
	v_mfma_f32_16x16x32_bf16 v[24:27], v[140:143], v[196:199], v[24:27]
	v_mfma_f32_16x16x32_bf16 v[12:15], v[132:135], v[204:207], v[12:15]
	v_mfma_f32_16x16x32_bf16 v[8:11], v[140:143], v[204:207], v[8:11]
	v_mfma_f32_16x16x32_bf16 v[52:55], v[156:159], v[176:179], v[52:55]
	v_mfma_f32_16x16x32_bf16 v[48:51], v[168:171], v[176:179], v[48:51]
	v_mfma_f32_16x16x32_bf16 v[36:39], v[156:159], v[184:187], v[36:39]
	v_mfma_f32_16x16x32_bf16 v[32:35], v[168:171], v[184:187], v[32:35]
	v_mfma_f32_16x16x32_bf16 v[20:23], v[156:159], v[192:195], v[20:23]
	v_mfma_f32_16x16x32_bf16 v[16:19], v[168:171], v[192:195], v[16:19]
	v_mfma_f32_16x16x32_bf16 v[4:7], v[156:159], v[200:203], v[4:7]
	v_mfma_f32_16x16x32_bf16 v[0:3], v[168:171], v[200:203], v[0:3]
	v_mfma_f32_16x16x32_bf16 v[52:55], v[164:167], v[180:183], v[52:55]
	v_mfma_f32_16x16x32_bf16 v[48:51], v[172:175], v[180:183], v[48:51]
	v_mfma_f32_16x16x32_bf16 v[36:39], v[164:167], v[188:191], v[36:39]
	v_mfma_f32_16x16x32_bf16 v[32:35], v[172:175], v[188:191], v[32:35]
	v_mfma_f32_16x16x32_bf16 v[20:23], v[164:167], v[196:199], v[20:23]
	v_mfma_f32_16x16x32_bf16 v[16:19], v[172:175], v[196:199], v[16:19]
	v_mfma_f32_16x16x32_bf16 v[4:7], v[164:167], v[204:207], v[4:7]
	v_mfma_f32_16x16x32_bf16 v[0:3], v[172:175], v[204:207], v[0:3]
	s_barrier
	ds_read_b128 v[128:131], v246 offset:32768
	ds_read_b128 v[132:135], v246 offset:33792
	ds_read_b128 v[136:139], v246 offset:34816
	ds_read_b128 v[140:143], v246 offset:35840
	ds_read_b128 v[156:159], v246 offset:49152
	ds_read_b128 v[164:167], v246 offset:50176
	ds_read_b128 v[168:171], v246 offset:51200
	ds_read_b128 v[172:175], v246 offset:52224
	s_add_u32 s64, s64, 0x4000
	s_addc_u32 s65, s65, 0
	s_mov_b32 m0, s41
	ds_read_b128 v[176:179], v163 offset:32768
	ds_read_b128 v[180:183], v163 offset:33792
	ds_read_b128 v[184:187], v163 offset:34816
	ds_read_b128 v[188:191], v163 offset:35840
	ds_read_b128 v[192:195], v163 offset:36864
	ds_read_b128 v[196:199], v163 offset:37888
	ds_read_b128 v[200:203], v163 offset:38912
	ds_read_b128 v[204:207], v163 offset:39936
	global_load_lds_dwordx4 v150, s[64:65]
	s_mov_b32 m0, s42
	s_nop 0
	global_load_lds_dwordx4 v146, s[64:65]
	s_waitcnt vmcnt(8) lgkmcnt(0)
	s_barrier
; #define PG8_STAGE(bufoff, gbase, voff) do { _Pragma("unroll") for (int _i = 0; _i < 2; ++_i) \
;         __builtin_amdgcn_global_load_lds((const unsigned*)((const char*)(gbase) + (voff)[_i]), (PG8_LAS unsigned*)(lds + (bufoff) + ldsw + _i * 8192), 16, 0, 0); } while (0)
; #define PG8_LDA(dst, b, h) do { _Pragma("unroll") for (int m = 0; m < 4; ++m) _Pragma("unroll") for (int k = 0; k < 2; ++k) dst[m][k] = *(const PG8_LAS bf16x8*)(lds + PG8_SA(b, h) + aoff + m * 2048 + k * 1024); } while (0)
; #define PG8_MMA(ai, bj, At, Bt) do { __builtin_amdgcn_s_setprio(1); _Pragma("unroll") for (int m = 0; m < 4; ++m) _Pragma("unroll") for (int n = 0; n < 2; ++n) _Pragma("unroll") for (int k = 0; k < 2; ++k) \
;         acc[ai][bj][m][n] = __builtin_amdgcn_mfma_f32_16x16x32_bf16(Bt[n][k], At[m][k], acc[ai][bj][m][n], 0, 0, 0); __builtin_amdgcn_s_setprio(0); } while (0)
; #define PG8_WAIT_V(n) asm volatile("s_waitcnt vmcnt(" #n ")" ::: "memory")
; #define PG8_WAIT_L(n) asm volatile("s_waitcnt lgkmcnt(" #n ")" ::: "memory")
; #define PG8_BAR __builtin_amdgcn_s_barrier()
; #define PG8_SCHED __builtin_amdgcn_sched_barrier(0)
; template <class Epi, class Sched, bool ALIGN_EPI = false, bool SP2 = false>
; __device__ __forceinline__ void gemm_phase(PG8_LAS unsigned char* lds, const Gemm g, const Sched& S, const Epi& E) {
;     ...
;             PG8_WAIT_V(8); PG8_WAIT_L(0); PG8_BAR; PG8_MMA(0, 0, At, B0); PG8_MMA(0, 1, At, B1); PG8_BAR; PG8_SCHED;
;             PG8_LDA(At, 1, 1); PG8_STAGE(PG8_SB(1, 0), b3, voffB); PG8_STAGE(PG8_SB(1, 1), b3 + hstep, voffB); PG8_STAGE(PG8_SA(1, 0), a3, voffA);
;             PG8_WAIT_V(8); PG8_WAIT_L(0); PG8_BAR; PG8_MMA(1, 0, At, B0); PG8_MMA(1, 1, At, B1); PG8_BAR; PG8_SCHED;
	v_mfma_f32_16x16x32_bf16 v[124:127], v[128:131], v[176:179], v[124:127]
	v_mfma_f32_16x16x32_bf16 v[120:123], v[136:139], v[176:179], v[120:123]
	v_mfma_f32_16x16x32_bf16 v[108:111], v[128:131], v[184:187], v[108:111]
	v_mfma_f32_16x16x32_bf16 v[104:107], v[136:139], v[184:187], v[104:107]
	v_mfma_f32_16x16x32_bf16 v[92:95], v[128:131], v[192:195], v[92:95]
	v_mfma_f32_16x16x32_bf16 v[88:91], v[136:139], v[192:195], v[88:91]
	v_mfma_f32_16x16x32_bf16 v[76:79], v[128:131], v[200:203], v[76:79]
	v_mfma_f32_16x16x32_bf16 v[72:75], v[136:139], v[200:203], v[72:75]
	v_mfma_f32_16x16x32_bf16 v[124:127], v[132:135], v[180:183], v[124:127]
	v_mfma_f32_16x16x32_bf16 v[120:123], v[140:143], v[180:183], v[120:123]
	v_mfma_f32_16x16x32_bf16 v[108:111], v[132:135], v[188:191], v[108:111]
	v_mfma_f32_16x16x32_bf16 v[104:107], v[140:143], v[188:191], v[104:107]
	v_mfma_f32_16x16x32_bf16 v[92:95], v[132:135], v[196:199], v[92:95]
	v_mfma_f32_16x16x32_bf16 v[88:91], v[140:143], v[196:199], v[88:91]
	v_mfma_f32_16x16x32_bf16 v[76:79], v[132:135], v[204:207], v[76:79]
	v_mfma_f32_16x16x32_bf16 v[72:75], v[140:143], v[204:207], v[72:75]
	v_mfma_f32_16x16x32_bf16 v[116:119], v[156:159], v[176:179], v[116:119]
	v_mfma_f32_16x16x32_bf16 v[112:115], v[168:171], v[176:179], v[112:115]
	v_mfma_f32_16x16x32_bf16 v[100:103], v[156:159], v[184:187], v[100:103]
	v_mfma_f32_16x16x32_bf16 v[96:99], v[168:171], v[184:187], v[96:99]
	v_mfma_f32_16x16x32_bf16 v[84:87], v[156:159], v[192:195], v[84:87]
	v_mfma_f32_16x16x32_bf16 v[80:83], v[168:171], v[192:195], v[80:83]
	v_mfma_f32_16x16x32_bf16 v[68:71], v[156:159], v[200:203], v[68:71]
	v_mfma_f32_16x16x32_bf16 v[64:67], v[168:171], v[200:203], v[64:67]
	v_mfma_f32_16x16x32_bf16 v[116:119], v[164:167], v[180:183], v[116:119]
	v_mfma_f32_16x16x32_bf16 v[112:115], v[172:175], v[180:183], v[112:115]
	v_mfma_f32_16x16x32_bf16 v[100:103], v[164:167], v[188:191], v[100:103]
	v_mfma_f32_16x16x32_bf16 v[96:99], v[172:175], v[188:191], v[96:99]
	v_mfma_f32_16x16x32_bf16 v[84:87], v[164:167], v[196:199], v[84:87]
	v_mfma_f32_16x16x32_bf16 v[80:83], v[172:175], v[196:199], v[80:83]
	v_mfma_f32_16x16x32_bf16 v[68:71], v[164:167], v[204:207], v[68:71]
	v_mfma_f32_16x16x32_bf16 v[64:67], v[172:175], v[204:207], v[64:67]
	s_barrier
	s_add_u32 s64, s62, 0x8000
	s_addc_u32 s65, s63, 0
	s_add_i32 m0, s30, 0x18000
	ds_read_b128 v[176:179], v163 offset:49152
	ds_read_b128 v[180:183], v163 offset:50176
	ds_read_b128 v[184:187], v163 offset:51200
	ds_read_b128 v[188:191], v163 offset:52224
	ds_read_b128 v[192:195], v163 offset:53248
	ds_read_b128 v[196:199], v163 offset:54272
	ds_read_b128 v[200:203], v163 offset:55296
	ds_read_b128 v[204:207], v163 offset:56320
	global_load_lds_dwordx4 v148, s[64:65]
	s_add_i32 m0, s30, 0x1a000
	s_add_u32 s62, s62, 0xc000
	s_addc_u32 s63, s63, 0
	global_load_lds_dwordx4 v144, s[64:65]
	s_add_i32 m0, s30, 0x1c000
	s_nop 0
	global_load_lds_dwordx4 v148, s[62:63]
	s_add_i32 m0, s30, 0x1e000
	s_nop 0
	global_load_lds_dwordx4 v144, s[62:63]
	s_mov_b32 m0, s54
	s_nop 0
	global_load_lds_dwordx4 v150, s[20:21]
	s_mov_b32 m0, s55
	s_nop 0
	global_load_lds_dwordx4 v146, s[20:21]
	s_waitcnt vmcnt(8) lgkmcnt(0)
	s_barrier
	v_mfma_f32_16x16x32_bf16 v[60:63], v[128:131], v[176:179], v[60:63]
	v_mfma_f32_16x16x32_bf16 v[56:59], v[136:139], v[176:179], v[56:59]
	v_mfma_f32_16x16x32_bf16 v[44:47], v[128:131], v[184:187], v[44:47]
	v_mfma_f32_16x16x32_bf16 v[40:43], v[136:139], v[184:187], v[40:43]
	v_mfma_f32_16x16x32_bf16 v[28:31], v[128:131], v[192:195], v[28:31]
	v_mfma_f32_16x16x32_bf16 v[24:27], v[136:139], v[192:195], v[24:27]
	v_mfma_f32_16x16x32_bf16 v[12:15], v[128:131], v[200:203], v[12:15]
	v_mfma_f32_16x16x32_bf16 v[8:11], v[136:139], v[200:203], v[8:11]
	v_mfma_f32_16x16x32_bf16 v[60:63], v[132:135], v[180:183], v[60:63]
	v_mfma_f32_16x16x32_bf16 v[56:59], v[140:143], v[180:183], v[56:59]
	v_mfma_f32_16x16x32_bf16 v[44:47], v[132:135], v[188:191], v[44:47]
	v_mfma_f32_16x16x32_bf16 v[40:43], v[140:143], v[188:191], v[40:43]
	v_mfma_f32_16x16x32_bf16 v[28:31], v[132:135], v[196:199], v[28:31]
	v_mfma_f32_16x16x32_bf16 v[24:27], v[140:143], v[196:199], v[24:27]
	v_mfma_f32_16x16x32_bf16 v[12:15], v[132:135], v[204:207], v[12:15]
	v_mfma_f32_16x16x32_bf16 v[8:11], v[140:143], v[204:207], v[8:11]
	v_mfma_f32_16x16x32_bf16 v[52:55], v[156:159], v[176:179], v[52:55]
	v_mfma_f32_16x16x32_bf16 v[48:51], v[168:171], v[176:179], v[48:51]
	v_mfma_f32_16x16x32_bf16 v[36:39], v[156:159], v[184:187], v[36:39]
	v_mfma_f32_16x16x32_bf16 v[32:35], v[168:171], v[184:187], v[32:35]
	v_mfma_f32_16x16x32_bf16 v[20:23], v[156:159], v[192:195], v[20:23]
	v_mfma_f32_16x16x32_bf16 v[16:19], v[168:171], v[192:195], v[16:19]
	v_mfma_f32_16x16x32_bf16 v[4:7], v[156:159], v[200:203], v[4:7]
	v_mfma_f32_16x16x32_bf16 v[0:3], v[168:171], v[200:203], v[0:3]
	v_mfma_f32_16x16x32_bf16 v[52:55], v[164:167], v[180:183], v[52:55]
	v_mfma_f32_16x16x32_bf16 v[48:51], v[172:175], v[180:183], v[48:51]
	v_mfma_f32_16x16x32_bf16 v[36:39], v[164:167], v[188:191], v[36:39]
	v_mfma_f32_16x16x32_bf16 v[32:35], v[172:175], v[188:191], v[32:35]
	v_mfma_f32_16x16x32_bf16 v[20:23], v[164:167], v[196:199], v[20:23]
	v_mfma_f32_16x16x32_bf16 v[16:19], v[172:175], v[196:199], v[16:19]
	v_mfma_f32_16x16x32_bf16 v[4:7], v[164:167], v[204:207], v[4:7]
	v_mfma_f32_16x16x32_bf16 v[0:3], v[172:175], v[204:207], v[0:3]
	s_barrier
	s_add_i32 s68, s68, 2
	s_add_u32 s18, s18, 0x10000
	s_addc_u32 s19, s19, 0
	s_add_u32 s66, s66, 0x10000
	s_addc_u32 s67, s67, 0
	s_cmp_gt_u32 s68, 13
	s_cbranch_scc0 .LBB0_1356
	s_and_b64 vcc, exec, s[6:7]
	s_cbranch_vccz .LBB0_1359
	s_barrier
